# v29 plus snake MFMA order inside each 8-MFMA group of the GEMM K-loops (pure permutation, same dependency distances)
# baseline (speedup 1.0000x reference)
; #define PG8_STAGE(bufoff, gbase, voff) do { _Pragma("unroll") for (int _i = 0; _i < 2; ++_i) \
;         __builtin_amdgcn_global_load_lds((const unsigned*)((const char*)(gbase) + (voff)[_i]), (PG8_LAS unsigned*)(lds + (bufoff) + ldsw + _i * 8192), 16, 0, 0); } while (0)
; #define PG8_LDA(dst, b, h) do { _Pragma("unroll") for (int m = 0; m < 4; ++m) _Pragma("unroll") for (int k = 0; k < 2; ++k) dst[m][k] = *(const PG8_LAS bf16x8*)(lds + PG8_SA(b, h) + aoff + m * 2048 + k * 1024); } while (0)
; #define PG8_LDB(dst, b, h) do { _Pragma("unroll") for (int n = 0; n < 2; ++n) _Pragma("unroll") for (int k = 0; k < 2; ++k) dst[n][k] = *(const PG8_LAS bf16x8*)(lds + PG8_SB(b, h) + boff + n * 2048 + k * 1024); } while (0)
; #define PG8_MMA(ai, bj, At, Bt) do { __builtin_amdgcn_s_setprio(1); _Pragma("unroll") for (int m = 0; m < 4; ++m) _Pragma("unroll") for (int n = 0; n < 2; ++n) _Pragma("unroll") for (int k = 0; k < 2; ++k) \
;         acc[ai][bj][m][n] = __builtin_amdgcn_mfma_f32_16x16x32_bf16(Bt[n][k], At[m][k], acc[ai][bj][m][n], 0, 0, 0); __builtin_amdgcn_s_setprio(0); } while (0)
; #define PG8_WAIT_V(n) asm volatile("s_waitcnt vmcnt(" #n ")" ::: "memory")
; template <class Epi, class Sched, bool ALIGN_EPI = false, bool SP2 = false>
; __device__ __forceinline__ void gemm_phase(PG8_LAS unsigned char* lds, const Gemm g, const Sched& S, const Epi& E) {
;     ...
;             PG8_LDB(B0, 0, 0); PG8_LDB(B1, 0, 1); PG8_SCHED; PG8_LDA(At, 0, 0); PG8_STAGE(PG8_SA(1, 1), a1 + hstep, voffA);
;             PG8_WAIT_V(8); PG8_WAIT_L(0); PG8_BAR; PG8_MMA(0, 0, At, B0); PG8_MMA(0, 1, At, B1); PG8_BAR; PG8_SCHED;
;             PG8_LDA(At, 0, 1); PG8_STAGE(PG8_SB(0, 0), b2, voffB); PG8_STAGE(PG8_SB(0, 1), b2 + hstep, voffB); PG8_STAGE(PG8_SA(0, 0), a2, voffA);
;             PG8_WAIT_V(8); PG8_WAIT_L(0); PG8_BAR; PG8_MMA(1, 0, At, B0); PG8_MMA(1, 1, At, B1); PG8_BAR; PG8_SCHED;
;             PG8_LDB(B0, 1, 0); PG8_LDB(B1, 1, 1); PG8_SCHED; PG8_LDA(At, 1, 0); PG8_STAGE(PG8_SA(0, 1), a2 + hstep, voffA);
;             PG8_WAIT_V(8); PG8_WAIT_L(0); PG8_BAR; PG8_MMA(0, 0, At, B0); PG8_MMA(0, 1, At, B1); PG8_BAR; PG8_SCHED;
;             PG8_LDA(At, 1, 1); PG8_STAGE(PG8_SB(1, 0), b3, voffB); PG8_STAGE(PG8_SB(1, 1), b3 + hstep, voffB); PG8_STAGE(PG8_SA(1, 0), a3, voffA);
;             PG8_WAIT_V(8); PG8_WAIT_L(0); PG8_BAR; PG8_MMA(1, 0, At, B0); PG8_MMA(1, 1, At, B1); PG8_BAR; PG8_SCHED;
.LBB0_139:
	ds_read_b128 v[2:5], v187
	ds_read_b128 v[6:9], v187 offset:1024
	ds_read_b128 v[138:141], v187 offset:2048
	ds_read_b128 v[142:145], v187 offset:3072
	ds_read_b128 v[146:149], v197
	ds_read_b128 v[150:153], v197 offset:1024
	ds_read_b128 v[154:157], v197 offset:2048
	ds_read_b128 v[158:161], v197 offset:3072
	s_add_u32 s14, s12, 0xfff00080
	s_addc_u32 s15, s13, -1
	s_cmp_eq_u32 s33, 60
	s_cselect_b32 s17, s2, s15
	s_cselect_b32 s16, s11, s14
	s_cselect_b32 s15, s26, s30
	s_cselect_b32 s14, s28, s29
	v_lshl_add_u64 v[162:163], s[12:13], 0, v[188:189]
	s_add_i32 m0, s27, 0xc000
	ds_read_b128 v[202:205], v199
	ds_read_b128 v[206:209], v199 offset:1024
	ds_read_b128 v[214:217], v199 offset:2048
	ds_read_b128 v[218:221], v199 offset:3072
	ds_read_b128 v[222:225], v199 offset:4096
	ds_read_b128 v[226:229], v199 offset:5120
	ds_read_b128 v[230:233], v199 offset:6144
	ds_read_b128 v[234:237], v199 offset:7168
	global_load_lds_dwordx4 v[162:163], off
	v_lshl_add_u64 v[162:163], s[12:13], 0, v[190:191]
	s_add_i32 m0, s27, 0xe000
	s_nop 0
	global_load_lds_dwordx4 v[162:163], off
	s_waitcnt vmcnt(8)
	s_waitcnt lgkmcnt(0)
	s_setprio 1
	s_barrier
	v_mfma_f32_16x16x32_bf16 v[134:137], v[2:5], v[202:205], v[134:137]
	v_mfma_f32_16x16x32_bf16 v[130:133], v[138:141], v[202:205], v[130:133]
	v_mfma_f32_16x16x32_bf16 v[114:117], v[138:141], v[214:217], v[114:117]
	v_mfma_f32_16x16x32_bf16 v[118:121], v[2:5], v[214:217], v[118:121]
	v_mfma_f32_16x16x32_bf16 v[102:105], v[2:5], v[222:225], v[102:105]
	v_mfma_f32_16x16x32_bf16 v[98:101], v[138:141], v[222:225], v[98:101]
	v_mfma_f32_16x16x32_bf16 v[82:85], v[138:141], v[230:233], v[82:85]
	v_mfma_f32_16x16x32_bf16 v[86:89], v[2:5], v[230:233], v[86:89]
	v_mfma_f32_16x16x32_bf16 v[134:137], v[6:9], v[206:209], v[134:137]
	v_mfma_f32_16x16x32_bf16 v[130:133], v[142:145], v[206:209], v[130:133]
	v_mfma_f32_16x16x32_bf16 v[114:117], v[142:145], v[218:221], v[114:117]
	v_mfma_f32_16x16x32_bf16 v[118:121], v[6:9], v[218:221], v[118:121]
	v_mfma_f32_16x16x32_bf16 v[102:105], v[6:9], v[226:229], v[102:105]
	v_mfma_f32_16x16x32_bf16 v[98:101], v[142:145], v[226:229], v[98:101]
	v_mfma_f32_16x16x32_bf16 v[82:85], v[142:145], v[234:237], v[82:85]
	v_mfma_f32_16x16x32_bf16 v[86:89], v[6:9], v[234:237], v[86:89]
	s_setprio 0
	s_setprio 1
	v_mfma_f32_16x16x32_bf16 v[126:129], v[146:149], v[202:205], v[126:129]
	v_mfma_f32_16x16x32_bf16 v[122:125], v[154:157], v[202:205], v[122:125]
	v_mfma_f32_16x16x32_bf16 v[106:109], v[154:157], v[214:217], v[106:109]
	v_mfma_f32_16x16x32_bf16 v[110:113], v[146:149], v[214:217], v[110:113]
	v_mfma_f32_16x16x32_bf16 v[94:97], v[146:149], v[222:225], v[94:97]
	v_mfma_f32_16x16x32_bf16 v[90:93], v[154:157], v[222:225], v[90:93]
	v_mfma_f32_16x16x32_bf16 v[74:77], v[154:157], v[230:233], v[74:77]
	v_mfma_f32_16x16x32_bf16 v[78:81], v[146:149], v[230:233], v[78:81]
	v_mfma_f32_16x16x32_bf16 v[126:129], v[150:153], v[206:209], v[126:129]
	v_mfma_f32_16x16x32_bf16 v[122:125], v[158:161], v[206:209], v[122:125]
	v_mfma_f32_16x16x32_bf16 v[106:109], v[158:161], v[218:221], v[106:109]
	v_mfma_f32_16x16x32_bf16 v[110:113], v[150:153], v[218:221], v[110:113]
	v_mfma_f32_16x16x32_bf16 v[94:97], v[150:153], v[226:229], v[94:97]
	v_mfma_f32_16x16x32_bf16 v[90:93], v[158:161], v[226:229], v[90:93]
	v_mfma_f32_16x16x32_bf16 v[74:77], v[158:161], v[234:237], v[74:77]
	v_mfma_f32_16x16x32_bf16 v[78:81], v[150:153], v[234:237], v[78:81]
	s_barrier
	s_setprio 0
	s_add_i32 s34, s41, s25
	v_lshl_add_u64 v[162:163], s[14:15], 0, v[168:169]
	s_mov_b32 m0, s34
	ds_read_b128 v[202:205], v199 offset:16384
	ds_read_b128 v[206:209], v199 offset:17408
	ds_read_b128 v[214:217], v199 offset:18432
	ds_read_b128 v[218:221], v199 offset:19456
	ds_read_b128 v[222:225], v199 offset:20480
	ds_read_b128 v[226:229], v199 offset:21504
	ds_read_b128 v[230:233], v199 offset:22528
	ds_read_b128 v[234:237], v199 offset:23552
	global_load_lds_dwordx4 v[162:163], off
	s_add_i32 m0, s34, 0x2000
	s_add_u32 s34, s14, 0x100000
	v_lshl_add_u64 v[210:211], s[14:15], 0, v[172:173]
	s_addc_u32 s35, s15, 0
	s_add_i32 s79, s92, s25
	global_load_lds_dwordx4 v[210:211], off
	v_lshl_add_u64 v[238:239], s[34:35], 0, v[168:169]
	s_mov_b32 m0, s79
	v_lshl_add_u64 v[240:241], s[16:17], 0, v[170:171]
	global_load_lds_dwordx4 v[238:239], off
	v_lshl_add_u64 v[238:239], s[34:35], 0, v[172:173]
	s_add_i32 m0, s79, 0x2000
	s_nop 0
	global_load_lds_dwordx4 v[238:239], off
	v_lshl_add_u64 v[238:239], s[16:17], 0, v[164:165]
	s_mov_b32 m0, s27
	s_nop 0
	global_load_lds_dwordx4 v[238:239], off
	s_mov_b32 m0, s39
	s_nop 0
	global_load_lds_dwordx4 v[240:241], off
	s_waitcnt vmcnt(8)
	s_waitcnt lgkmcnt(0)
	s_setprio 1
	s_barrier
; #define PG8_STAGE(bufoff, gbase, voff) do { _Pragma("unroll") for (int _i = 0; _i < 2; ++_i) \
;         __builtin_amdgcn_global_load_lds((const unsigned*)((const char*)(gbase) + (voff)[_i]), (PG8_LAS unsigned*)(lds + (bufoff) + ldsw + _i * 8192), 16, 0, 0); } while (0)
; #define PG8_LDA(dst, b, h) do { _Pragma("unroll") for (int m = 0; m < 4; ++m) _Pragma("unroll") for (int k = 0; k < 2; ++k) dst[m][k] = *(const PG8_LAS bf16x8*)(lds + PG8_SA(b, h) + aoff + m * 2048 + k * 1024); } while (0)
; #define PG8_LDB(dst, b, h) do { _Pragma("unroll") for (int n = 0; n < 2; ++n) _Pragma("unroll") for (int k = 0; k < 2; ++k) dst[n][k] = *(const PG8_LAS bf16x8*)(lds + PG8_SB(b, h) + boff + n * 2048 + k * 1024); } while (0)
; #define PG8_MMA(ai, bj, At, Bt) do { __builtin_amdgcn_s_setprio(1); _Pragma("unroll") for (int m = 0; m < 4; ++m) _Pragma("unroll") for (int n = 0; n < 2; ++n) _Pragma("unroll") for (int k = 0; k < 2; ++k) \
;         acc[ai][bj][m][n] = __builtin_amdgcn_mfma_f32_16x16x32_bf16(Bt[n][k], At[m][k], acc[ai][bj][m][n], 0, 0, 0); __builtin_amdgcn_s_setprio(0); } while (0)
; #define PG8_WAIT_V(n) asm volatile("s_waitcnt vmcnt(" #n ")" ::: "memory")
; template <class Epi, class Sched, bool ALIGN_EPI = false, bool SP2 = false>
; __device__ __forceinline__ void gemm_phase(PG8_LAS unsigned char* lds, const Gemm g, const Sched& S, const Epi& E) {
;     ...
;             PG8_LDB(B0, 0, 0); PG8_LDB(B1, 0, 1); PG8_SCHED; PG8_LDA(At, 0, 0); PG8_STAGE(PG8_SA(1, 1), a1 + hstep, voffA);
;             PG8_WAIT_V(8); PG8_WAIT_L(0); PG8_BAR; PG8_MMA(0, 0, At, B0); PG8_MMA(0, 1, At, B1); PG8_BAR; PG8_SCHED;
;             PG8_LDA(At, 0, 1); PG8_STAGE(PG8_SB(0, 0), b2, voffB); PG8_STAGE(PG8_SB(0, 1), b2 + hstep, voffB); PG8_STAGE(PG8_SA(0, 0), a2, voffA);
;             PG8_WAIT_V(8); PG8_WAIT_L(0); PG8_BAR; PG8_MMA(1, 0, At, B0); PG8_MMA(1, 1, At, B1); PG8_BAR; PG8_SCHED;
;             PG8_LDB(B0, 1, 0); PG8_LDB(B1, 1, 1); PG8_SCHED; PG8_LDA(At, 1, 0); PG8_STAGE(PG8_SA(0, 1), a2 + hstep, voffA);
;             PG8_WAIT_V(8); PG8_WAIT_L(0); PG8_BAR; PG8_MMA(0, 0, At, B0); PG8_MMA(0, 1, At, B1); PG8_BAR; PG8_SCHED;
;             PG8_LDA(At, 1, 1); PG8_STAGE(PG8_SB(1, 0), b3, voffB); PG8_STAGE(PG8_SB(1, 1), b3 + hstep, voffB); PG8_STAGE(PG8_SA(1, 0), a3, voffA);
;             PG8_WAIT_V(8); PG8_WAIT_L(0); PG8_BAR; PG8_MMA(1, 0, At, B0); PG8_MMA(1, 1, At, B1); PG8_BAR; PG8_SCHED;
	v_mfma_f32_16x16x32_bf16 v[70:73], v[2:5], v[202:205], v[70:73]
	v_mfma_f32_16x16x32_bf16 v[66:69], v[138:141], v[202:205], v[66:69]
	v_mfma_f32_16x16x32_bf16 v[54:57], v[2:5], v[214:217], v[54:57]
	v_mfma_f32_16x16x32_bf16 v[50:53], v[138:141], v[214:217], v[50:53]
	v_mfma_f32_16x16x32_bf16 v[38:41], v[2:5], v[222:225], v[38:41]
	v_mfma_f32_16x16x32_bf16 v[34:37], v[138:141], v[222:225], v[34:37]
	v_mfma_f32_16x16x32_bf16 v[2:5], v[2:5], v[230:233], v[22:25]
	v_mfma_f32_16x16x32_bf16 v[70:73], v[6:9], v[206:209], v[70:73]
	v_mfma_f32_16x16x32_bf16 v[66:69], v[142:145], v[206:209], v[66:69]
	v_mfma_f32_16x16x32_bf16 v[54:57], v[6:9], v[218:221], v[54:57]
	v_mfma_f32_16x16x32_bf16 v[50:53], v[142:145], v[218:221], v[50:53]
	v_mfma_f32_16x16x32_bf16 v[38:41], v[6:9], v[226:229], v[38:41]
	v_mfma_f32_16x16x32_bf16 v[34:37], v[142:145], v[226:229], v[34:37]
	v_mfma_f32_16x16x32_bf16 v[2:5], v[6:9], v[234:237], v[2:5]
	v_mfma_f32_16x16x32_bf16 v[6:9], v[138:141], v[230:233], v[18:21]
	v_mfma_f32_16x16x32_bf16 v[6:9], v[142:145], v[234:237], v[6:9]
	s_setprio 0
	s_setprio 1
	v_mfma_f32_16x16x32_bf16 v[18:21], v[146:149], v[202:205], v[62:65]
	v_mfma_f32_16x16x32_bf16 v[62:65], v[150:153], v[206:209], v[18:21]
	v_mfma_f32_16x16x32_bf16 v[18:21], v[154:157], v[202:205], v[58:61]
	v_mfma_f32_16x16x32_bf16 v[58:61], v[158:161], v[206:209], v[18:21]
	v_mfma_f32_16x16x32_bf16 v[18:21], v[146:149], v[214:217], v[46:49]
	v_mfma_f32_16x16x32_bf16 v[46:49], v[150:153], v[218:221], v[18:21]
	v_mfma_f32_16x16x32_bf16 v[18:21], v[154:157], v[214:217], v[42:45]
	v_mfma_f32_16x16x32_bf16 v[42:45], v[158:161], v[218:221], v[18:21]
	v_mfma_f32_16x16x32_bf16 v[18:21], v[146:149], v[222:225], v[30:33]
	v_mfma_f32_16x16x32_bf16 v[30:33], v[150:153], v[226:229], v[18:21]
	v_mfma_f32_16x16x32_bf16 v[18:21], v[154:157], v[222:225], v[26:29]
	v_mfma_f32_16x16x32_bf16 v[14:17], v[146:149], v[230:233], v[14:17]
	v_mfma_f32_16x16x32_bf16 v[10:13], v[154:157], v[230:233], v[10:13]
	v_mfma_f32_16x16x32_bf16 v[26:29], v[158:161], v[226:229], v[18:21]
	v_mfma_f32_16x16x32_bf16 v[14:17], v[150:153], v[234:237], v[14:17]
	v_mfma_f32_16x16x32_bf16 v[10:13], v[158:161], v[234:237], v[10:13]
	s_barrier
	s_setprio 0
	s_add_i32 s34, 0, 0x18000
	s_add_i32 s35, 0, 0x1c000
	v_add_u32_e32 v142, s34, v179
	v_add_u32_e32 v158, s35, v179
	ds_read_b128 v[18:21], v142
	ds_read_b128 v[22:25], v142 offset:1024
	ds_read_b128 v[138:141], v142 offset:2048
	ds_read_b128 v[142:145], v142 offset:3072
	ds_read_b128 v[146:149], v158
	ds_read_b128 v[150:153], v158 offset:1024
	ds_read_b128 v[154:157], v158 offset:2048
	ds_read_b128 v[158:161], v158 offset:3072
	s_add_u32 s16, s16, 0x100000
	s_addc_u32 s17, s17, 0
	s_mov_b32 m0, s71
	v_lshl_add_u64 v[242:243], s[16:17], 0, v[164:165]
	ds_read_b128 v[202:205], v199 offset:32768
	ds_read_b128 v[206:209], v199 offset:33792
	ds_read_b128 v[214:217], v199 offset:34816
	ds_read_b128 v[218:221], v199 offset:35840
	ds_read_b128 v[222:225], v199 offset:36864
	ds_read_b128 v[226:229], v199 offset:37888
	ds_read_b128 v[230:233], v199 offset:38912
	ds_read_b128 v[234:237], v199 offset:39936
	global_load_lds_dwordx4 v[242:243], off
	v_lshl_add_u64 v[242:243], s[16:17], 0, v[170:171]
	s_mov_b32 m0, s87
	s_nop 0
	global_load_lds_dwordx4 v[242:243], off
	s_waitcnt vmcnt(8)
	s_waitcnt lgkmcnt(0)
	s_setprio 1
	s_barrier
	v_mfma_f32_16x16x32_bf16 v[134:137], v[18:21], v[202:205], v[134:137]
	v_mfma_f32_16x16x32_bf16 v[130:133], v[138:141], v[202:205], v[130:133]
	v_mfma_f32_16x16x32_bf16 v[114:117], v[138:141], v[214:217], v[114:117]
	v_mfma_f32_16x16x32_bf16 v[118:121], v[18:21], v[214:217], v[118:121]
	v_mfma_f32_16x16x32_bf16 v[102:105], v[18:21], v[222:225], v[102:105]
	v_mfma_f32_16x16x32_bf16 v[98:101], v[138:141], v[222:225], v[98:101]
	v_mfma_f32_16x16x32_bf16 v[82:85], v[138:141], v[230:233], v[82:85]
	v_mfma_f32_16x16x32_bf16 v[86:89], v[18:21], v[230:233], v[86:89]
	v_mfma_f32_16x16x32_bf16 v[134:137], v[22:25], v[206:209], v[134:137]
	v_mfma_f32_16x16x32_bf16 v[130:133], v[142:145], v[206:209], v[130:133]
	v_mfma_f32_16x16x32_bf16 v[114:117], v[142:145], v[218:221], v[114:117]
	v_mfma_f32_16x16x32_bf16 v[118:121], v[22:25], v[218:221], v[118:121]
	v_mfma_f32_16x16x32_bf16 v[102:105], v[22:25], v[226:229], v[102:105]
	v_mfma_f32_16x16x32_bf16 v[98:101], v[142:145], v[226:229], v[98:101]
	v_mfma_f32_16x16x32_bf16 v[82:85], v[142:145], v[234:237], v[82:85]
	v_mfma_f32_16x16x32_bf16 v[86:89], v[22:25], v[234:237], v[86:89]
	s_setprio 0
	s_setprio 1
	v_mfma_f32_16x16x32_bf16 v[126:129], v[146:149], v[202:205], v[126:129]
	v_mfma_f32_16x16x32_bf16 v[122:125], v[154:157], v[202:205], v[122:125]
	v_mfma_f32_16x16x32_bf16 v[106:109], v[154:157], v[214:217], v[106:109]
	v_mfma_f32_16x16x32_bf16 v[110:113], v[146:149], v[214:217], v[110:113]
	v_mfma_f32_16x16x32_bf16 v[94:97], v[146:149], v[222:225], v[94:97]
	v_mfma_f32_16x16x32_bf16 v[90:93], v[154:157], v[222:225], v[90:93]
	v_mfma_f32_16x16x32_bf16 v[74:77], v[154:157], v[230:233], v[74:77]
	v_mfma_f32_16x16x32_bf16 v[78:81], v[146:149], v[230:233], v[78:81]
	v_mfma_f32_16x16x32_bf16 v[126:129], v[150:153], v[206:209], v[126:129]
	v_mfma_f32_16x16x32_bf16 v[122:125], v[158:161], v[206:209], v[122:125]
	v_mfma_f32_16x16x32_bf16 v[106:109], v[158:161], v[218:221], v[106:109]
	v_mfma_f32_16x16x32_bf16 v[110:113], v[150:153], v[218:221], v[110:113]
	v_mfma_f32_16x16x32_bf16 v[94:97], v[150:153], v[226:229], v[94:97]
	v_mfma_f32_16x16x32_bf16 v[90:93], v[158:161], v[226:229], v[90:93]
	v_mfma_f32_16x16x32_bf16 v[74:77], v[158:161], v[234:237], v[74:77]
	v_mfma_f32_16x16x32_bf16 v[78:81], v[150:153], v[234:237], v[78:81]
	s_barrier
; #define PG8_STAGE(bufoff, gbase, voff) do { _Pragma("unroll") for (int _i = 0; _i < 2; ++_i) \
;         __builtin_amdgcn_global_load_lds((const unsigned*)((const char*)(gbase) + (voff)[_i]), (PG8_LAS unsigned*)(lds + (bufoff) + ldsw + _i * 8192), 16, 0, 0); } while (0)
; #define PG8_LDA(dst, b, h) do { _Pragma("unroll") for (int m = 0; m < 4; ++m) _Pragma("unroll") for (int k = 0; k < 2; ++k) dst[m][k] = *(const PG8_LAS bf16x8*)(lds + PG8_SA(b, h) + aoff + m * 2048 + k * 1024); } while (0)
; #define PG8_LDB(dst, b, h) do { _Pragma("unroll") for (int n = 0; n < 2; ++n) _Pragma("unroll") for (int k = 0; k < 2; ++k) dst[n][k] = *(const PG8_LAS bf16x8*)(lds + PG8_SB(b, h) + boff + n * 2048 + k * 1024); } while (0)
; #define PG8_MMA(ai, bj, At, Bt) do { __builtin_amdgcn_s_setprio(1); _Pragma("unroll") for (int m = 0; m < 4; ++m) _Pragma("unroll") for (int n = 0; n < 2; ++n) _Pragma("unroll") for (int k = 0; k < 2; ++k) \
;         acc[ai][bj][m][n] = __builtin_amdgcn_mfma_f32_16x16x32_bf16(Bt[n][k], At[m][k], acc[ai][bj][m][n], 0, 0, 0); __builtin_amdgcn_s_setprio(0); } while (0)
; #define PG8_WAIT_V(n) asm volatile("s_waitcnt vmcnt(" #n ")" ::: "memory")
; template <class Epi, class Sched, bool ALIGN_EPI = false, bool SP2 = false>
; __device__ __forceinline__ void gemm_phase(PG8_LAS unsigned char* lds, const Gemm g, const Sched& S, const Epi& E) {
;     ...
;             PG8_LDB(B0, 0, 0); PG8_LDB(B1, 0, 1); PG8_SCHED; PG8_LDA(At, 0, 0); PG8_STAGE(PG8_SA(1, 1), a1 + hstep, voffA);
;             PG8_WAIT_V(8); PG8_WAIT_L(0); PG8_BAR; PG8_MMA(0, 0, At, B0); PG8_MMA(0, 1, At, B1); PG8_BAR; PG8_SCHED;
;             PG8_LDA(At, 0, 1); PG8_STAGE(PG8_SB(0, 0), b2, voffB); PG8_STAGE(PG8_SB(0, 1), b2 + hstep, voffB); PG8_STAGE(PG8_SA(0, 0), a2, voffA);
;             PG8_WAIT_V(8); PG8_WAIT_L(0); PG8_BAR; PG8_MMA(1, 0, At, B0); PG8_MMA(1, 1, At, B1); PG8_BAR; PG8_SCHED;
;             PG8_LDB(B0, 1, 0); PG8_LDB(B1, 1, 1); PG8_SCHED; PG8_LDA(At, 1, 0); PG8_STAGE(PG8_SA(0, 1), a2 + hstep, voffA);
;             PG8_WAIT_V(8); PG8_WAIT_L(0); PG8_BAR; PG8_MMA(0, 0, At, B0); PG8_MMA(0, 1, At, B1); PG8_BAR; PG8_SCHED;
;             PG8_LDA(At, 1, 1); PG8_STAGE(PG8_SB(1, 0), b3, voffB); PG8_STAGE(PG8_SB(1, 1), b3 + hstep, voffB); PG8_STAGE(PG8_SA(1, 0), a3, voffA);
;             PG8_WAIT_V(8); PG8_WAIT_L(0); PG8_BAR; PG8_MMA(1, 0, At, B0); PG8_MMA(1, 1, At, B1); PG8_BAR; PG8_SCHED;
	s_setprio 0
	s_add_i32 s16, s34, s25
	v_lshl_add_u64 v[162:163], v[162:163], 0, s[46:47]
	s_mov_b32 m0, s16
	ds_read_b128 v[202:205], v199 offset:49152
	ds_read_b128 v[206:209], v199 offset:50176
	ds_read_b128 v[214:217], v199 offset:51200
	ds_read_b128 v[218:221], v199 offset:52224
	ds_read_b128 v[222:225], v199 offset:53248
	ds_read_b128 v[226:229], v199 offset:54272
	ds_read_b128 v[230:233], v199 offset:55296
	ds_read_b128 v[234:237], v199 offset:56320
	global_load_lds_dwordx4 v[162:163], off
	s_add_i32 m0, s16, 0x2000
	s_add_u32 s14, s14, 0x100080
	v_lshl_add_u64 v[162:163], v[210:211], 0, s[46:47]
	s_addc_u32 s15, s15, 0
	s_add_i32 s16, s35, s25
	global_load_lds_dwordx4 v[162:163], off
	v_lshl_add_u64 v[162:163], s[14:15], 0, v[168:169]
	s_mov_b32 m0, s16
	s_nop 0
	global_load_lds_dwordx4 v[162:163], off
	v_lshl_add_u64 v[162:163], s[14:15], 0, v[172:173]
	s_add_i32 m0, s16, 0x2000
	s_nop 0
	global_load_lds_dwordx4 v[162:163], off
	v_lshl_add_u64 v[162:163], v[238:239], 0, s[46:47]
	s_mov_b32 m0, s95
	s_nop 0
	global_load_lds_dwordx4 v[162:163], off
	v_lshl_add_u64 v[162:163], v[240:241], 0, s[46:47]
	s_mov_b32 m0, s96
	s_nop 0
	global_load_lds_dwordx4 v[162:163], off
	s_waitcnt vmcnt(8)
	s_waitcnt lgkmcnt(0)
	s_setprio 1
	s_barrier
	v_mfma_f32_16x16x32_bf16 v[70:73], v[18:21], v[202:205], v[70:73]
	v_mfma_f32_16x16x32_bf16 v[54:57], v[18:21], v[214:217], v[54:57]
	v_mfma_f32_16x16x32_bf16 v[38:41], v[18:21], v[222:225], v[38:41]
	v_mfma_f32_16x16x32_bf16 v[2:5], v[18:21], v[230:233], v[2:5]
	v_mfma_f32_16x16x32_bf16 v[70:73], v[22:25], v[206:209], v[70:73]
	v_mfma_f32_16x16x32_bf16 v[66:69], v[138:141], v[202:205], v[66:69]
	v_mfma_f32_16x16x32_bf16 v[54:57], v[22:25], v[218:221], v[54:57]
	v_mfma_f32_16x16x32_bf16 v[50:53], v[138:141], v[214:217], v[50:53]
	v_mfma_f32_16x16x32_bf16 v[38:41], v[22:25], v[226:229], v[38:41]
	v_mfma_f32_16x16x32_bf16 v[34:37], v[138:141], v[222:225], v[34:37]
	v_mfma_f32_16x16x32_bf16 v[22:25], v[22:25], v[234:237], v[2:5]
	v_mfma_f32_16x16x32_bf16 v[2:5], v[138:141], v[230:233], v[6:9]
	v_mfma_f32_16x16x32_bf16 v[66:69], v[142:145], v[206:209], v[66:69]
	v_mfma_f32_16x16x32_bf16 v[50:53], v[142:145], v[218:221], v[50:53]
	v_mfma_f32_16x16x32_bf16 v[34:37], v[142:145], v[226:229], v[34:37]
	v_mfma_f32_16x16x32_bf16 v[18:21], v[142:145], v[234:237], v[2:5]
	s_setprio 0
	s_setprio 1
	v_mfma_f32_16x16x32_bf16 v[2:5], v[146:149], v[202:205], v[62:65]
	v_mfma_f32_16x16x32_bf16 v[62:65], v[150:153], v[206:209], v[2:5]
	v_mfma_f32_16x16x32_bf16 v[2:5], v[154:157], v[202:205], v[58:61]
	v_mfma_f32_16x16x32_bf16 v[58:61], v[158:161], v[206:209], v[2:5]
	v_mfma_f32_16x16x32_bf16 v[2:5], v[146:149], v[214:217], v[46:49]
	v_mfma_f32_16x16x32_bf16 v[46:49], v[150:153], v[218:221], v[2:5]
	v_mfma_f32_16x16x32_bf16 v[2:5], v[154:157], v[214:217], v[42:45]
	v_mfma_f32_16x16x32_bf16 v[42:45], v[158:161], v[218:221], v[2:5]
	v_mfma_f32_16x16x32_bf16 v[2:5], v[146:149], v[222:225], v[30:33]
	v_mfma_f32_16x16x32_bf16 v[30:33], v[150:153], v[226:229], v[2:5]
	v_mfma_f32_16x16x32_bf16 v[2:5], v[154:157], v[222:225], v[26:29]
	v_mfma_f32_16x16x32_bf16 v[26:29], v[158:161], v[226:229], v[2:5]
	v_mfma_f32_16x16x32_bf16 v[2:5], v[146:149], v[230:233], v[14:17]
	v_mfma_f32_16x16x32_bf16 v[14:17], v[150:153], v[234:237], v[2:5]
	v_mfma_f32_16x16x32_bf16 v[2:5], v[154:157], v[230:233], v[10:13]
	v_mfma_f32_16x16x32_bf16 v[10:13], v[158:161], v[234:237], v[2:5]
	s_barrier
	s_setprio 0
	s_add_i32 s33, s33, 2
	s_add_u32 s12, s12, 0x100
	s_addc_u32 s13, s13, 0
	s_add_u32 s29, s29, 0x100
	s_addc_u32 s30, s30, 0
	s_cmp_gt_u32 s33, 61
	s_cbranch_scc0 .LBB0_139
	s_and_b64 vcc, exec, s[48:49]
	s_cbranch_vccz .LBB0_142
	s_barrier

; #define PG8_STAGE(bufoff, gbase, voff) do { _Pragma("unroll") for (int _i = 0; _i < 2; ++_i) \
;         __builtin_amdgcn_global_load_lds((const unsigned*)((const char*)(gbase) + (voff)[_i]), (PG8_LAS unsigned*)(lds + (bufoff) + ldsw + _i * 8192), 16, 0, 0); } while (0)
; #define PG8_LDA(dst, b, h) do { _Pragma("unroll") for (int m = 0; m < 4; ++m) _Pragma("unroll") for (int k = 0; k < 2; ++k) dst[m][k] = *(const PG8_LAS bf16x8*)(lds + PG8_SA(b, h) + aoff + m * 2048 + k * 1024); } while (0)
; #define PG8_LDB(dst, b, h) do { _Pragma("unroll") for (int n = 0; n < 2; ++n) _Pragma("unroll") for (int k = 0; k < 2; ++k) dst[n][k] = *(const PG8_LAS bf16x8*)(lds + PG8_SB(b, h) + boff + n * 2048 + k * 1024); } while (0)
; #define PG8_MMA(ai, bj, At, Bt) do { __builtin_amdgcn_s_setprio(1); _Pragma("unroll") for (int m = 0; m < 4; ++m) _Pragma("unroll") for (int n = 0; n < 2; ++n) _Pragma("unroll") for (int k = 0; k < 2; ++k) \
;         acc[ai][bj][m][n] = __builtin_amdgcn_mfma_f32_16x16x32_bf16(Bt[n][k], At[m][k], acc[ai][bj][m][n], 0, 0, 0); __builtin_amdgcn_s_setprio(0); } while (0)
; #define PG8_WAIT_V(n) asm volatile("s_waitcnt vmcnt(" #n ")" ::: "memory")
; template <class Epi, class Sched, bool ALIGN_EPI = false, bool SP2 = false>
; __device__ __forceinline__ void gemm_phase(PG8_LAS unsigned char* lds, const Gemm g, const Sched& S, const Epi& E) {
;     ...
;             PG8_LDB(B0, 0, 0); PG8_LDB(B1, 0, 1); PG8_SCHED; PG8_LDA(At, 0, 0); PG8_STAGE(PG8_SA(1, 1), a1 + hstep, voffA);
;             PG8_WAIT_V(8); PG8_WAIT_L(0); PG8_BAR; PG8_MMA(0, 0, At, B0); PG8_MMA(0, 1, At, B1); PG8_BAR; PG8_SCHED;
;             PG8_LDA(At, 0, 1); PG8_STAGE(PG8_SB(0, 0), b2, voffB); PG8_STAGE(PG8_SB(0, 1), b2 + hstep, voffB); PG8_STAGE(PG8_SA(0, 0), a2, voffA);
;             PG8_WAIT_V(8); PG8_WAIT_L(0); PG8_BAR; PG8_MMA(1, 0, At, B0); PG8_MMA(1, 1, At, B1); PG8_BAR; PG8_SCHED;
;             PG8_LDB(B0, 1, 0); PG8_LDB(B1, 1, 1); PG8_SCHED; PG8_LDA(At, 1, 0); PG8_STAGE(PG8_SA(0, 1), a2 + hstep, voffA);
;             PG8_WAIT_V(8); PG8_WAIT_L(0); PG8_BAR; PG8_MMA(0, 0, At, B0); PG8_MMA(0, 1, At, B1); PG8_BAR; PG8_SCHED;
;             PG8_LDA(At, 1, 1); PG8_STAGE(PG8_SB(1, 0), b3, voffB); PG8_STAGE(PG8_SB(1, 1), b3 + hstep, voffB); PG8_STAGE(PG8_SA(1, 0), a3, voffA);
;             PG8_WAIT_V(8); PG8_WAIT_L(0); PG8_BAR; PG8_MMA(1, 0, At, B0); PG8_MMA(1, 1, At, B1); PG8_BAR; PG8_SCHED;
.LBB0_1062:
	ds_read_b128 v[146:149], v155
	ds_read_b128 v[158:161], v155 offset:1024
	ds_read_b128 v[168:171], v155 offset:2048
	ds_read_b128 v[172:175], v155 offset:3072
	ds_read_b128 v[176:179], v156
	ds_read_b128 v[180:183], v156 offset:1024
	ds_read_b128 v[184:187], v156 offset:2048
	ds_read_b128 v[188:191], v156 offset:3072
	s_add_u32 s72, s70, 0xfff80080
	s_addc_u32 s73, s71, -1
	s_cmp_eq_u32 s77, 28
	s_cselect_b32 s75, s34, s73
	s_cselect_b32 s74, s35, s72
	s_cselect_b32 s73, s61, s76
	s_cselect_b32 s72, s63, s69
	v_lshl_add_u64 v[150:151], s[70:71], 0, v[138:139]
	s_add_i32 m0, s25, 0xc000
	ds_read_b128 v[200:203], v157
	ds_read_b128 v[204:207], v157 offset:1024
	ds_read_b128 v[208:211], v157 offset:2048
	ds_read_b128 v[212:215], v157 offset:3072
	ds_read_b128 v[216:219], v157 offset:4096
	ds_read_b128 v[220:223], v157 offset:5120
	ds_read_b128 v[224:227], v157 offset:6144
	ds_read_b128 v[228:231], v157 offset:7168
	global_load_lds_dwordx4 v[150:151], off
	v_lshl_add_u64 v[150:151], s[70:71], 0, v[140:141]
	s_add_i32 m0, s25, 0xe000
	s_nop 0
	global_load_lds_dwordx4 v[150:151], off
	s_waitcnt vmcnt(8)
	s_waitcnt lgkmcnt(0)
	s_setprio 1
	s_barrier
	v_mfma_f32_16x16x32_bf16 v[126:129], v[146:149], v[200:203], v[126:129]
	v_mfma_f32_16x16x32_bf16 v[122:125], v[168:171], v[200:203], v[122:125]
	v_mfma_f32_16x16x32_bf16 v[106:109], v[168:171], v[208:211], v[106:109]
	v_mfma_f32_16x16x32_bf16 v[110:113], v[146:149], v[208:211], v[110:113]
	v_mfma_f32_16x16x32_bf16 v[94:97], v[146:149], v[216:219], v[94:97]
	v_mfma_f32_16x16x32_bf16 v[90:93], v[168:171], v[216:219], v[90:93]
	v_mfma_f32_16x16x32_bf16 v[74:77], v[168:171], v[224:227], v[74:77]
	v_mfma_f32_16x16x32_bf16 v[78:81], v[146:149], v[224:227], v[78:81]
	v_mfma_f32_16x16x32_bf16 v[126:129], v[158:161], v[204:207], v[126:129]
	v_mfma_f32_16x16x32_bf16 v[122:125], v[172:175], v[204:207], v[122:125]
	v_mfma_f32_16x16x32_bf16 v[106:109], v[172:175], v[212:215], v[106:109]
	v_mfma_f32_16x16x32_bf16 v[110:113], v[158:161], v[212:215], v[110:113]
	v_mfma_f32_16x16x32_bf16 v[94:97], v[158:161], v[220:223], v[94:97]
	v_mfma_f32_16x16x32_bf16 v[90:93], v[172:175], v[220:223], v[90:93]
	v_mfma_f32_16x16x32_bf16 v[74:77], v[172:175], v[228:231], v[74:77]
	v_mfma_f32_16x16x32_bf16 v[78:81], v[158:161], v[228:231], v[78:81]
	s_setprio 0
	s_setprio 1
	v_mfma_f32_16x16x32_bf16 v[118:121], v[176:179], v[200:203], v[118:121]
	v_mfma_f32_16x16x32_bf16 v[114:117], v[184:187], v[200:203], v[114:117]
	v_mfma_f32_16x16x32_bf16 v[98:101], v[184:187], v[208:211], v[98:101]
	v_mfma_f32_16x16x32_bf16 v[102:105], v[176:179], v[208:211], v[102:105]
	v_mfma_f32_16x16x32_bf16 v[86:89], v[176:179], v[216:219], v[86:89]
	v_mfma_f32_16x16x32_bf16 v[82:85], v[184:187], v[216:219], v[82:85]
	v_mfma_f32_16x16x32_bf16 v[66:69], v[184:187], v[224:227], v[66:69]
	v_mfma_f32_16x16x32_bf16 v[70:73], v[176:179], v[224:227], v[70:73]
	v_mfma_f32_16x16x32_bf16 v[118:121], v[180:183], v[204:207], v[118:121]
	v_mfma_f32_16x16x32_bf16 v[114:117], v[188:191], v[204:207], v[114:117]
	v_mfma_f32_16x16x32_bf16 v[98:101], v[188:191], v[212:215], v[98:101]
	v_mfma_f32_16x16x32_bf16 v[102:105], v[180:183], v[212:215], v[102:105]
	v_mfma_f32_16x16x32_bf16 v[86:89], v[180:183], v[220:223], v[86:89]
	v_mfma_f32_16x16x32_bf16 v[82:85], v[188:191], v[220:223], v[82:85]
	v_mfma_f32_16x16x32_bf16 v[66:69], v[188:191], v[228:231], v[66:69]
	v_mfma_f32_16x16x32_bf16 v[70:73], v[180:183], v[228:231], v[70:73]
	s_barrier
	s_setprio 0
	s_add_i32 s78, s31, s2
	v_lshl_add_u64 v[150:151], s[72:73], 0, v[134:135]
	s_mov_b32 m0, s78
	ds_read_b128 v[200:203], v157 offset:16384
	ds_read_b128 v[204:207], v157 offset:17408
	ds_read_b128 v[208:211], v157 offset:18432
	ds_read_b128 v[212:215], v157 offset:19456
	ds_read_b128 v[216:219], v157 offset:20480
	ds_read_b128 v[220:223], v157 offset:21504
	ds_read_b128 v[224:227], v157 offset:22528
	ds_read_b128 v[228:231], v157 offset:23552
	global_load_lds_dwordx4 v[150:151], off
	s_add_i32 m0, s78, 0x2000
	s_add_u32 s78, s72, 0x80000
	v_lshl_add_u64 v[162:163], s[72:73], 0, v[130:131]
	s_addc_u32 s79, s73, 0
	s_add_i32 s80, s40, s2
	global_load_lds_dwordx4 v[162:163], off
	v_lshl_add_u64 v[192:193], s[78:79], 0, v[134:135]
	s_mov_b32 m0, s80
	v_lshl_add_u64 v[232:233], s[74:75], 0, v[132:133]
	global_load_lds_dwordx4 v[192:193], off
	v_lshl_add_u64 v[192:193], s[78:79], 0, v[130:131]
	s_add_i32 m0, s80, 0x2000
	s_nop 0
	global_load_lds_dwordx4 v[192:193], off
	v_lshl_add_u64 v[192:193], s[74:75], 0, v[136:137]
	s_mov_b32 m0, s25
	s_nop 0
	global_load_lds_dwordx4 v[192:193], off
	s_mov_b32 m0, s26
	s_nop 0
	global_load_lds_dwordx4 v[232:233], off
	s_waitcnt vmcnt(8)
	s_waitcnt lgkmcnt(0)
	s_setprio 1
	s_barrier
; #define PG8_STAGE(bufoff, gbase, voff) do { _Pragma("unroll") for (int _i = 0; _i < 2; ++_i) \
;         __builtin_amdgcn_global_load_lds((const unsigned*)((const char*)(gbase) + (voff)[_i]), (PG8_LAS unsigned*)(lds + (bufoff) + ldsw + _i * 8192), 16, 0, 0); } while (0)
; #define PG8_LDA(dst, b, h) do { _Pragma("unroll") for (int m = 0; m < 4; ++m) _Pragma("unroll") for (int k = 0; k < 2; ++k) dst[m][k] = *(const PG8_LAS bf16x8*)(lds + PG8_SA(b, h) + aoff + m * 2048 + k * 1024); } while (0)
; #define PG8_LDB(dst, b, h) do { _Pragma("unroll") for (int n = 0; n < 2; ++n) _Pragma("unroll") for (int k = 0; k < 2; ++k) dst[n][k] = *(const PG8_LAS bf16x8*)(lds + PG8_SB(b, h) + boff + n * 2048 + k * 1024); } while (0)
; #define PG8_MMA(ai, bj, At, Bt) do { __builtin_amdgcn_s_setprio(1); _Pragma("unroll") for (int m = 0; m < 4; ++m) _Pragma("unroll") for (int n = 0; n < 2; ++n) _Pragma("unroll") for (int k = 0; k < 2; ++k) \
;         acc[ai][bj][m][n] = __builtin_amdgcn_mfma_f32_16x16x32_bf16(Bt[n][k], At[m][k], acc[ai][bj][m][n], 0, 0, 0); __builtin_amdgcn_s_setprio(0); } while (0)
; #define PG8_WAIT_V(n) asm volatile("s_waitcnt vmcnt(" #n ")" ::: "memory")
; template <class Epi, class Sched, bool ALIGN_EPI = false, bool SP2 = false>
; __device__ __forceinline__ void gemm_phase(PG8_LAS unsigned char* lds, const Gemm g, const Sched& S, const Epi& E) {
;     ...
;             PG8_LDB(B0, 0, 0); PG8_LDB(B1, 0, 1); PG8_SCHED; PG8_LDA(At, 0, 0); PG8_STAGE(PG8_SA(1, 1), a1 + hstep, voffA);
;             PG8_WAIT_V(8); PG8_WAIT_L(0); PG8_BAR; PG8_MMA(0, 0, At, B0); PG8_MMA(0, 1, At, B1); PG8_BAR; PG8_SCHED;
;             PG8_LDA(At, 0, 1); PG8_STAGE(PG8_SB(0, 0), b2, voffB); PG8_STAGE(PG8_SB(0, 1), b2 + hstep, voffB); PG8_STAGE(PG8_SA(0, 0), a2, voffA);
;             PG8_WAIT_V(8); PG8_WAIT_L(0); PG8_BAR; PG8_MMA(1, 0, At, B0); PG8_MMA(1, 1, At, B1); PG8_BAR; PG8_SCHED;
;             PG8_LDB(B0, 1, 0); PG8_LDB(B1, 1, 1); PG8_SCHED; PG8_LDA(At, 1, 0); PG8_STAGE(PG8_SA(0, 1), a2 + hstep, voffA);
;             PG8_WAIT_V(8); PG8_WAIT_L(0); PG8_BAR; PG8_MMA(0, 0, At, B0); PG8_MMA(0, 1, At, B1); PG8_BAR; PG8_SCHED;
;             PG8_LDA(At, 1, 1); PG8_STAGE(PG8_SB(1, 0), b3, voffB); PG8_STAGE(PG8_SB(1, 1), b3 + hstep, voffB); PG8_STAGE(PG8_SA(1, 0), a3, voffA);
;             PG8_WAIT_V(8); PG8_WAIT_L(0); PG8_BAR; PG8_MMA(1, 0, At, B0); PG8_MMA(1, 1, At, B1); PG8_BAR; PG8_SCHED;
	v_mfma_f32_16x16x32_bf16 v[62:65], v[146:149], v[200:203], v[62:65]
	v_mfma_f32_16x16x32_bf16 v[58:61], v[168:171], v[200:203], v[58:61]
	v_mfma_f32_16x16x32_bf16 v[42:45], v[168:171], v[208:211], v[42:45]
	v_mfma_f32_16x16x32_bf16 v[46:49], v[146:149], v[208:211], v[46:49]
	v_mfma_f32_16x16x32_bf16 v[30:33], v[146:149], v[216:219], v[30:33]
	v_mfma_f32_16x16x32_bf16 v[26:29], v[168:171], v[216:219], v[26:29]
	v_mfma_f32_16x16x32_bf16 v[10:13], v[168:171], v[224:227], v[10:13]
	v_mfma_f32_16x16x32_bf16 v[14:17], v[146:149], v[224:227], v[14:17]
	v_mfma_f32_16x16x32_bf16 v[62:65], v[158:161], v[204:207], v[62:65]
	v_mfma_f32_16x16x32_bf16 v[58:61], v[172:175], v[204:207], v[58:61]
	v_mfma_f32_16x16x32_bf16 v[42:45], v[172:175], v[212:215], v[42:45]
	v_mfma_f32_16x16x32_bf16 v[46:49], v[158:161], v[212:215], v[46:49]
	v_mfma_f32_16x16x32_bf16 v[30:33], v[158:161], v[220:223], v[30:33]
	v_mfma_f32_16x16x32_bf16 v[26:29], v[172:175], v[220:223], v[26:29]
	v_mfma_f32_16x16x32_bf16 v[10:13], v[172:175], v[228:231], v[10:13]
	v_mfma_f32_16x16x32_bf16 v[14:17], v[158:161], v[228:231], v[14:17]
	s_setprio 0
	s_setprio 1
	v_mfma_f32_16x16x32_bf16 v[54:57], v[176:179], v[200:203], v[54:57]
	v_mfma_f32_16x16x32_bf16 v[50:53], v[184:187], v[200:203], v[50:53]
	v_mfma_f32_16x16x32_bf16 v[34:37], v[184:187], v[208:211], v[34:37]
	v_mfma_f32_16x16x32_bf16 v[38:41], v[176:179], v[208:211], v[38:41]
	v_mfma_f32_16x16x32_bf16 v[22:25], v[176:179], v[216:219], v[22:25]
	v_mfma_f32_16x16x32_bf16 v[18:21], v[184:187], v[216:219], v[18:21]
	v_mfma_f32_16x16x32_bf16 v[2:5], v[184:187], v[224:227], v[2:5]
	v_mfma_f32_16x16x32_bf16 v[6:9], v[176:179], v[224:227], v[6:9]
	v_mfma_f32_16x16x32_bf16 v[54:57], v[180:183], v[204:207], v[54:57]
	v_mfma_f32_16x16x32_bf16 v[50:53], v[188:191], v[204:207], v[50:53]
	v_mfma_f32_16x16x32_bf16 v[34:37], v[188:191], v[212:215], v[34:37]
	v_mfma_f32_16x16x32_bf16 v[38:41], v[180:183], v[212:215], v[38:41]
	v_mfma_f32_16x16x32_bf16 v[22:25], v[180:183], v[220:223], v[22:25]
	v_mfma_f32_16x16x32_bf16 v[18:21], v[188:191], v[220:223], v[18:21]
	v_mfma_f32_16x16x32_bf16 v[2:5], v[188:191], v[228:231], v[2:5]
	v_mfma_f32_16x16x32_bf16 v[6:9], v[180:183], v[228:231], v[6:9]
	s_barrier
	s_setprio 0
	s_add_i32 s78, 0, 0x18000
	v_add_u32_e32 v166, s78, v153
	s_add_i32 s79, 0, 0x1c000
	ds_read_b128 v[146:149], v166
	ds_read_b128 v[158:161], v166 offset:1024
	ds_read_b128 v[168:171], v166 offset:2048
	ds_read_b128 v[172:175], v166 offset:3072
	v_add_u32_e32 v166, s79, v153
	ds_read_b128 v[176:179], v166
	ds_read_b128 v[180:183], v166 offset:1024
	ds_read_b128 v[184:187], v166 offset:2048
	ds_read_b128 v[188:191], v166 offset:3072
	s_add_u32 s74, s74, 0x80000
	s_addc_u32 s75, s75, 0
	s_mov_b32 m0, s27
	v_lshl_add_u64 v[240:241], s[74:75], 0, v[136:137]
	ds_read_b128 v[200:203], v157 offset:32768
	ds_read_b128 v[204:207], v157 offset:33792
	ds_read_b128 v[208:211], v157 offset:34816
	ds_read_b128 v[212:215], v157 offset:35840
	ds_read_b128 v[216:219], v157 offset:36864
	ds_read_b128 v[220:223], v157 offset:37888
	ds_read_b128 v[224:227], v157 offset:38912
	ds_read_b128 v[228:231], v157 offset:39936
	global_load_lds_dwordx4 v[240:241], off
	v_lshl_add_u64 v[240:241], s[74:75], 0, v[132:133]
	s_mov_b32 m0, s28
	s_nop 0
	global_load_lds_dwordx4 v[240:241], off
	s_waitcnt vmcnt(8)
	s_waitcnt lgkmcnt(0)
	s_setprio 1
	s_barrier
	v_mfma_f32_16x16x32_bf16 v[126:129], v[146:149], v[200:203], v[126:129]
	v_mfma_f32_16x16x32_bf16 v[122:125], v[168:171], v[200:203], v[122:125]
	v_mfma_f32_16x16x32_bf16 v[106:109], v[168:171], v[208:211], v[106:109]
	v_mfma_f32_16x16x32_bf16 v[110:113], v[146:149], v[208:211], v[110:113]
	v_mfma_f32_16x16x32_bf16 v[94:97], v[146:149], v[216:219], v[94:97]
	v_mfma_f32_16x16x32_bf16 v[90:93], v[168:171], v[216:219], v[90:93]
	v_mfma_f32_16x16x32_bf16 v[74:77], v[168:171], v[224:227], v[74:77]
	v_mfma_f32_16x16x32_bf16 v[78:81], v[146:149], v[224:227], v[78:81]
	v_mfma_f32_16x16x32_bf16 v[126:129], v[158:161], v[204:207], v[126:129]
	v_mfma_f32_16x16x32_bf16 v[122:125], v[172:175], v[204:207], v[122:125]
	v_mfma_f32_16x16x32_bf16 v[106:109], v[172:175], v[212:215], v[106:109]
	v_mfma_f32_16x16x32_bf16 v[110:113], v[158:161], v[212:215], v[110:113]
	v_mfma_f32_16x16x32_bf16 v[94:97], v[158:161], v[220:223], v[94:97]
	v_mfma_f32_16x16x32_bf16 v[90:93], v[172:175], v[220:223], v[90:93]
	v_mfma_f32_16x16x32_bf16 v[74:77], v[172:175], v[228:231], v[74:77]
	v_mfma_f32_16x16x32_bf16 v[78:81], v[158:161], v[228:231], v[78:81]
	s_setprio 0
	s_setprio 1
	v_mfma_f32_16x16x32_bf16 v[118:121], v[176:179], v[200:203], v[118:121]
	v_mfma_f32_16x16x32_bf16 v[114:117], v[184:187], v[200:203], v[114:117]
	v_mfma_f32_16x16x32_bf16 v[98:101], v[184:187], v[208:211], v[98:101]
	v_mfma_f32_16x16x32_bf16 v[102:105], v[176:179], v[208:211], v[102:105]
	v_mfma_f32_16x16x32_bf16 v[86:89], v[176:179], v[216:219], v[86:89]
	v_mfma_f32_16x16x32_bf16 v[82:85], v[184:187], v[216:219], v[82:85]
	v_mfma_f32_16x16x32_bf16 v[66:69], v[184:187], v[224:227], v[66:69]
	v_mfma_f32_16x16x32_bf16 v[70:73], v[176:179], v[224:227], v[70:73]
	v_mfma_f32_16x16x32_bf16 v[118:121], v[180:183], v[204:207], v[118:121]
	v_mfma_f32_16x16x32_bf16 v[114:117], v[188:191], v[204:207], v[114:117]
	v_mfma_f32_16x16x32_bf16 v[98:101], v[188:191], v[212:215], v[98:101]
	v_mfma_f32_16x16x32_bf16 v[102:105], v[180:183], v[212:215], v[102:105]
	v_mfma_f32_16x16x32_bf16 v[86:89], v[180:183], v[220:223], v[86:89]
	v_mfma_f32_16x16x32_bf16 v[82:85], v[188:191], v[220:223], v[82:85]
	v_mfma_f32_16x16x32_bf16 v[66:69], v[188:191], v[228:231], v[66:69]
	v_mfma_f32_16x16x32_bf16 v[70:73], v[180:183], v[228:231], v[70:73]
	s_barrier
; #define PG8_STAGE(bufoff, gbase, voff) do { _Pragma("unroll") for (int _i = 0; _i < 2; ++_i) \
;         __builtin_amdgcn_global_load_lds((const unsigned*)((const char*)(gbase) + (voff)[_i]), (PG8_LAS unsigned*)(lds + (bufoff) + ldsw + _i * 8192), 16, 0, 0); } while (0)
; #define PG8_LDA(dst, b, h) do { _Pragma("unroll") for (int m = 0; m < 4; ++m) _Pragma("unroll") for (int k = 0; k < 2; ++k) dst[m][k] = *(const PG8_LAS bf16x8*)(lds + PG8_SA(b, h) + aoff + m * 2048 + k * 1024); } while (0)
; #define PG8_MMA(ai, bj, At, Bt) do { __builtin_amdgcn_s_setprio(1); _Pragma("unroll") for (int m = 0; m < 4; ++m) _Pragma("unroll") for (int n = 0; n < 2; ++n) _Pragma("unroll") for (int k = 0; k < 2; ++k) \
;         acc[ai][bj][m][n] = __builtin_amdgcn_mfma_f32_16x16x32_bf16(Bt[n][k], At[m][k], acc[ai][bj][m][n], 0, 0, 0); __builtin_amdgcn_s_setprio(0); } while (0)
; #define PG8_WAIT_V(n) asm volatile("s_waitcnt vmcnt(" #n ")" ::: "memory")
; #define PG8_WAIT_L(n) asm volatile("s_waitcnt lgkmcnt(" #n ")" ::: "memory")
; #define PG8_BAR __builtin_amdgcn_s_barrier()
; #define PG8_SCHED __builtin_amdgcn_sched_barrier(0)
; template <class Epi, class Sched, bool ALIGN_EPI = false, bool SP2 = false>
; __device__ __forceinline__ void gemm_phase(PG8_LAS unsigned char* lds, const Gemm g, const Sched& S, const Epi& E) {
;     ...
;         for (int t = 0; t < nt; t += 2) {
;             const bool last = (t == nt - 2);
;             const char* a1 = cA + (size_t)(t + 1) * kstep;
;             const char* a2 = last ? nA : cA + (size_t)(t + 2) * kstep; const char* b2 = last ? nB : cB + (size_t)(t + 2) * kstep;
;     ...
;             PG8_LDA(At, 1, 1); PG8_STAGE(PG8_SB(1, 0), b3, voffB); PG8_STAGE(PG8_SB(1, 1), b3 + hstep, voffB); PG8_STAGE(PG8_SA(1, 0), a3, voffA);
;             PG8_WAIT_V(8); PG8_WAIT_L(0); PG8_BAR; PG8_MMA(1, 0, At, B0); PG8_MMA(1, 1, At, B1); PG8_BAR; PG8_SCHED;
	s_setprio 0
	s_add_i32 s74, s78, s2
	v_lshl_add_u64 v[150:151], v[150:151], 0, s[10:11]
	s_mov_b32 m0, s74
	ds_read_b128 v[200:203], v157 offset:49152
	ds_read_b128 v[204:207], v157 offset:50176
	ds_read_b128 v[208:211], v157 offset:51200
	ds_read_b128 v[212:215], v157 offset:52224
	ds_read_b128 v[216:219], v157 offset:53248
	ds_read_b128 v[220:223], v157 offset:54272
	ds_read_b128 v[224:227], v157 offset:55296
	ds_read_b128 v[228:231], v157 offset:56320
	global_load_lds_dwordx4 v[150:151], off
	s_add_i32 m0, s74, 0x2000
	s_add_u32 s72, s72, 0x80080
	v_lshl_add_u64 v[150:151], v[162:163], 0, s[10:11]
	s_addc_u32 s73, s73, 0
	s_add_i32 s74, s79, s2
	global_load_lds_dwordx4 v[150:151], off
	v_lshl_add_u64 v[150:151], s[72:73], 0, v[134:135]
	s_mov_b32 m0, s74
	s_nop 0
	global_load_lds_dwordx4 v[150:151], off
	v_lshl_add_u64 v[150:151], s[72:73], 0, v[130:131]
	s_add_i32 m0, s74, 0x2000
	s_nop 0
	global_load_lds_dwordx4 v[150:151], off
	v_lshl_add_u64 v[150:151], v[192:193], 0, s[10:11]
	s_mov_b32 m0, s30
	s_nop 0
	global_load_lds_dwordx4 v[150:151], off
	v_lshl_add_u64 v[150:151], v[232:233], 0, s[10:11]
	s_mov_b32 m0, s33
	s_nop 0
	global_load_lds_dwordx4 v[150:151], off
	s_waitcnt vmcnt(8)
	s_waitcnt lgkmcnt(0)
	s_setprio 1
	s_barrier
	v_mfma_f32_16x16x32_bf16 v[62:65], v[146:149], v[200:203], v[62:65]
	v_mfma_f32_16x16x32_bf16 v[58:61], v[168:171], v[200:203], v[58:61]
	v_mfma_f32_16x16x32_bf16 v[42:45], v[168:171], v[208:211], v[42:45]
	v_mfma_f32_16x16x32_bf16 v[46:49], v[146:149], v[208:211], v[46:49]
	v_mfma_f32_16x16x32_bf16 v[30:33], v[146:149], v[216:219], v[30:33]
	v_mfma_f32_16x16x32_bf16 v[26:29], v[168:171], v[216:219], v[26:29]
	v_mfma_f32_16x16x32_bf16 v[10:13], v[168:171], v[224:227], v[10:13]
	v_mfma_f32_16x16x32_bf16 v[14:17], v[146:149], v[224:227], v[14:17]
	v_mfma_f32_16x16x32_bf16 v[62:65], v[158:161], v[204:207], v[62:65]
	v_mfma_f32_16x16x32_bf16 v[58:61], v[172:175], v[204:207], v[58:61]
	v_mfma_f32_16x16x32_bf16 v[42:45], v[172:175], v[212:215], v[42:45]
	v_mfma_f32_16x16x32_bf16 v[46:49], v[158:161], v[212:215], v[46:49]
	v_mfma_f32_16x16x32_bf16 v[30:33], v[158:161], v[220:223], v[30:33]
	v_mfma_f32_16x16x32_bf16 v[26:29], v[172:175], v[220:223], v[26:29]
	v_mfma_f32_16x16x32_bf16 v[10:13], v[172:175], v[228:231], v[10:13]
	v_mfma_f32_16x16x32_bf16 v[14:17], v[158:161], v[228:231], v[14:17]
	s_setprio 0
	s_setprio 1
	v_mfma_f32_16x16x32_bf16 v[54:57], v[176:179], v[200:203], v[54:57]
	v_mfma_f32_16x16x32_bf16 v[50:53], v[184:187], v[200:203], v[50:53]
	v_mfma_f32_16x16x32_bf16 v[34:37], v[184:187], v[208:211], v[34:37]
	v_mfma_f32_16x16x32_bf16 v[38:41], v[176:179], v[208:211], v[38:41]
	v_mfma_f32_16x16x32_bf16 v[22:25], v[176:179], v[216:219], v[22:25]
	v_mfma_f32_16x16x32_bf16 v[18:21], v[184:187], v[216:219], v[18:21]
	v_mfma_f32_16x16x32_bf16 v[2:5], v[184:187], v[224:227], v[2:5]
	v_mfma_f32_16x16x32_bf16 v[6:9], v[176:179], v[224:227], v[6:9]
	v_mfma_f32_16x16x32_bf16 v[54:57], v[180:183], v[204:207], v[54:57]
	v_mfma_f32_16x16x32_bf16 v[50:53], v[188:191], v[204:207], v[50:53]
	v_mfma_f32_16x16x32_bf16 v[34:37], v[188:191], v[212:215], v[34:37]
	v_mfma_f32_16x16x32_bf16 v[38:41], v[180:183], v[212:215], v[38:41]
	v_mfma_f32_16x16x32_bf16 v[22:25], v[180:183], v[220:223], v[22:25]
	v_mfma_f32_16x16x32_bf16 v[18:21], v[188:191], v[220:223], v[18:21]
	v_mfma_f32_16x16x32_bf16 v[2:5], v[188:191], v[228:231], v[2:5]
	v_mfma_f32_16x16x32_bf16 v[6:9], v[180:183], v[228:231], v[6:9]
	s_barrier
	s_setprio 0
	s_add_i32 s77, s77, 2
	s_add_u32 s70, s70, 0x100
	s_addc_u32 s71, s71, 0
	s_add_u32 s69, s69, 0x100
	s_addc_u32 s76, s76, 0
	s_cmp_gt_u32 s77, 29
	s_cbranch_scc0 .LBB0_1062
	s_and_b64 vcc, exec, s[48:49]
	s_cbranch_vccz .LBB0_1065
	s_barrier

; #define PG8_STAGE(bufoff, gbase, voff) do { _Pragma("unroll") for (int _i = 0; _i < 2; ++_i) \
;         __builtin_amdgcn_global_load_lds((const unsigned*)((const char*)(gbase) + (voff)[_i]), (PG8_LAS unsigned*)(lds + (bufoff) + ldsw + _i * 8192), 16, 0, 0); } while (0)
; #define PG8_LDA(dst, b, h) do { _Pragma("unroll") for (int m = 0; m < 4; ++m) _Pragma("unroll") for (int k = 0; k < 2; ++k) dst[m][k] = *(const PG8_LAS bf16x8*)(lds + PG8_SA(b, h) + aoff + m * 2048 + k * 1024); } while (0)
; #define PG8_LDB(dst, b, h) do { _Pragma("unroll") for (int n = 0; n < 2; ++n) _Pragma("unroll") for (int k = 0; k < 2; ++k) dst[n][k] = *(const PG8_LAS bf16x8*)(lds + PG8_SB(b, h) + boff + n * 2048 + k * 1024); } while (0)
; #define PG8_MMA(ai, bj, At, Bt) do { __builtin_amdgcn_s_setprio(1); _Pragma("unroll") for (int m = 0; m < 4; ++m) _Pragma("unroll") for (int n = 0; n < 2; ++n) _Pragma("unroll") for (int k = 0; k < 2; ++k) \
;         acc[ai][bj][m][n] = __builtin_amdgcn_mfma_f32_16x16x32_bf16(Bt[n][k], At[m][k], acc[ai][bj][m][n], 0, 0, 0); __builtin_amdgcn_s_setprio(0); } while (0)
; #define PG8_WAIT_V(n) asm volatile("s_waitcnt vmcnt(" #n ")" ::: "memory")
; #define PG8_WAIT_L(n) asm volatile("s_waitcnt lgkmcnt(" #n ")" ::: "memory")
; template <class Epi, class Sched, bool ALIGN_EPI = false, bool SP2 = false>
; __device__ __forceinline__ void gemm_phase(PG8_LAS unsigned char* lds, const Gemm g, const Sched& S, const Epi& E) {
;     ...
;             const bool last = (t == nt - 2);
;             const char* a1 = cA + (size_t)(t + 1) * kstep;
;             const char* a2 = last ? nA : cA + (size_t)(t + 2) * kstep; const char* b2 = last ? nB : cB + (size_t)(t + 2) * kstep;
;             const char* a3 = a2 + kstep; const char* b3 = b2 + kstep;
;             if (last && has_next) S.a_ready(nxt);
;             if constexpr (SP2) {
;             PG8_LDB(B0, 0, 0); PG8_LDB(B1, 0, 1); PG8_SCHED; PG8_LDA(At, 0, 0); PG8_STAGE(PG8_SA(1, 1), a1 + hstep, voffA);
;             PG8_WAIT_V(8); PG8_WAIT_L(0); PG8_BAR; PG8_MMA(0, 0, At, B0); PG8_MMA(0, 1, At, B1); PG8_BAR; PG8_SCHED;
;             PG8_LDA(At, 0, 1); PG8_STAGE(PG8_SB(0, 0), b2, voffB); PG8_STAGE(PG8_SB(0, 1), b2 + hstep, voffB); PG8_STAGE(PG8_SA(0, 0), a2, voffA);
;             PG8_WAIT_V(8); PG8_WAIT_L(0); PG8_BAR; PG8_MMA(1, 0, At, B0); PG8_MMA(1, 1, At, B1); PG8_BAR; PG8_SCHED;
.LBB0_1078:
	ds_read_b128 v[146:149], v155
	ds_read_b128 v[158:161], v155 offset:1024
	ds_read_b128 v[168:171], v155 offset:2048
	ds_read_b128 v[172:175], v155 offset:3072
	ds_read_b128 v[176:179], v156
	ds_read_b128 v[180:183], v156 offset:1024
	ds_read_b128 v[184:187], v156 offset:2048
	ds_read_b128 v[188:191], v156 offset:3072
	s_add_u32 s68, s66, 0xfff80080
	s_addc_u32 s69, s67, -1
	s_cmp_eq_u32 s73, 28
	s_cselect_b32 s71, s34, s69
	s_cselect_b32 s70, s35, s68
	s_cselect_b32 s69, s57, s72
	s_cselect_b32 s68, s59, s65
	v_lshl_add_u64 v[150:151], s[66:67], 0, v[138:139]
	s_add_i32 m0, s25, 0xc000
	ds_read_b128 v[200:203], v157
	ds_read_b128 v[204:207], v157 offset:1024
	ds_read_b128 v[208:211], v157 offset:2048
	ds_read_b128 v[212:215], v157 offset:3072
	ds_read_b128 v[216:219], v157 offset:4096
	ds_read_b128 v[220:223], v157 offset:5120
	ds_read_b128 v[224:227], v157 offset:6144
	ds_read_b128 v[228:231], v157 offset:7168
	global_load_lds_dwordx4 v[150:151], off
	v_lshl_add_u64 v[150:151], s[66:67], 0, v[140:141]
	s_add_i32 m0, s25, 0xe000
	s_nop 0
	global_load_lds_dwordx4 v[150:151], off
	s_waitcnt vmcnt(8)
	s_waitcnt lgkmcnt(0)
	s_setprio 1
	s_barrier
	v_mfma_f32_16x16x32_bf16 v[126:129], v[146:149], v[200:203], v[126:129]
	v_mfma_f32_16x16x32_bf16 v[122:125], v[168:171], v[200:203], v[122:125]
	v_mfma_f32_16x16x32_bf16 v[106:109], v[168:171], v[208:211], v[106:109]
	v_mfma_f32_16x16x32_bf16 v[110:113], v[146:149], v[208:211], v[110:113]
	v_mfma_f32_16x16x32_bf16 v[94:97], v[146:149], v[216:219], v[94:97]
	v_mfma_f32_16x16x32_bf16 v[90:93], v[168:171], v[216:219], v[90:93]
	v_mfma_f32_16x16x32_bf16 v[74:77], v[168:171], v[224:227], v[74:77]
	v_mfma_f32_16x16x32_bf16 v[78:81], v[146:149], v[224:227], v[78:81]
	v_mfma_f32_16x16x32_bf16 v[126:129], v[158:161], v[204:207], v[126:129]
	v_mfma_f32_16x16x32_bf16 v[122:125], v[172:175], v[204:207], v[122:125]
	v_mfma_f32_16x16x32_bf16 v[106:109], v[172:175], v[212:215], v[106:109]
	v_mfma_f32_16x16x32_bf16 v[110:113], v[158:161], v[212:215], v[110:113]
	v_mfma_f32_16x16x32_bf16 v[94:97], v[158:161], v[220:223], v[94:97]
	v_mfma_f32_16x16x32_bf16 v[90:93], v[172:175], v[220:223], v[90:93]
	v_mfma_f32_16x16x32_bf16 v[74:77], v[172:175], v[228:231], v[74:77]
	v_mfma_f32_16x16x32_bf16 v[78:81], v[158:161], v[228:231], v[78:81]
	s_setprio 0
	s_setprio 1
	v_mfma_f32_16x16x32_bf16 v[118:121], v[176:179], v[200:203], v[118:121]
	v_mfma_f32_16x16x32_bf16 v[114:117], v[184:187], v[200:203], v[114:117]
	v_mfma_f32_16x16x32_bf16 v[98:101], v[184:187], v[208:211], v[98:101]
	v_mfma_f32_16x16x32_bf16 v[102:105], v[176:179], v[208:211], v[102:105]
	v_mfma_f32_16x16x32_bf16 v[86:89], v[176:179], v[216:219], v[86:89]
	v_mfma_f32_16x16x32_bf16 v[82:85], v[184:187], v[216:219], v[82:85]
	v_mfma_f32_16x16x32_bf16 v[66:69], v[184:187], v[224:227], v[66:69]
	v_mfma_f32_16x16x32_bf16 v[70:73], v[176:179], v[224:227], v[70:73]
	v_mfma_f32_16x16x32_bf16 v[118:121], v[180:183], v[204:207], v[118:121]
	v_mfma_f32_16x16x32_bf16 v[114:117], v[188:191], v[204:207], v[114:117]
	v_mfma_f32_16x16x32_bf16 v[98:101], v[188:191], v[212:215], v[98:101]
	v_mfma_f32_16x16x32_bf16 v[102:105], v[180:183], v[212:215], v[102:105]
	v_mfma_f32_16x16x32_bf16 v[86:89], v[180:183], v[220:223], v[86:89]
	v_mfma_f32_16x16x32_bf16 v[82:85], v[188:191], v[220:223], v[82:85]
	v_mfma_f32_16x16x32_bf16 v[66:69], v[188:191], v[228:231], v[66:69]
	v_mfma_f32_16x16x32_bf16 v[70:73], v[180:183], v[228:231], v[70:73]
	s_barrier
	s_setprio 0
	s_add_i32 s74, s31, s2
	v_lshl_add_u64 v[150:151], s[68:69], 0, v[134:135]
	s_mov_b32 m0, s74
	ds_read_b128 v[200:203], v157 offset:16384
	ds_read_b128 v[204:207], v157 offset:17408
	ds_read_b128 v[208:211], v157 offset:18432
	ds_read_b128 v[212:215], v157 offset:19456
	ds_read_b128 v[216:219], v157 offset:20480
	ds_read_b128 v[220:223], v157 offset:21504
	ds_read_b128 v[224:227], v157 offset:22528
	ds_read_b128 v[228:231], v157 offset:23552
	global_load_lds_dwordx4 v[150:151], off
	s_add_i32 m0, s74, 0x2000
	s_add_u32 s74, s68, 0x80000
	v_lshl_add_u64 v[162:163], s[68:69], 0, v[130:131]
	s_addc_u32 s75, s69, 0
	s_add_i32 s76, s40, s2
	global_load_lds_dwordx4 v[162:163], off
	v_lshl_add_u64 v[192:193], s[74:75], 0, v[134:135]
	s_mov_b32 m0, s76
	v_lshl_add_u64 v[232:233], s[70:71], 0, v[132:133]
	global_load_lds_dwordx4 v[192:193], off
	v_lshl_add_u64 v[192:193], s[74:75], 0, v[130:131]
	s_add_i32 m0, s76, 0x2000
	s_nop 0
	global_load_lds_dwordx4 v[192:193], off
	v_lshl_add_u64 v[192:193], s[70:71], 0, v[136:137]
	s_mov_b32 m0, s25
	s_nop 0
	global_load_lds_dwordx4 v[192:193], off
	s_mov_b32 m0, s26
	s_nop 0
	global_load_lds_dwordx4 v[232:233], off
	s_waitcnt vmcnt(8)
	s_waitcnt lgkmcnt(0)
	s_setprio 1
	s_barrier
; #define PG8_STAGE(bufoff, gbase, voff) do { _Pragma("unroll") for (int _i = 0; _i < 2; ++_i) \
;         __builtin_amdgcn_global_load_lds((const unsigned*)((const char*)(gbase) + (voff)[_i]), (PG8_LAS unsigned*)(lds + (bufoff) + ldsw + _i * 8192), 16, 0, 0); } while (0)
; #define PG8_LDA(dst, b, h) do { _Pragma("unroll") for (int m = 0; m < 4; ++m) _Pragma("unroll") for (int k = 0; k < 2; ++k) dst[m][k] = *(const PG8_LAS bf16x8*)(lds + PG8_SA(b, h) + aoff + m * 2048 + k * 1024); } while (0)
; #define PG8_LDB(dst, b, h) do { _Pragma("unroll") for (int n = 0; n < 2; ++n) _Pragma("unroll") for (int k = 0; k < 2; ++k) dst[n][k] = *(const PG8_LAS bf16x8*)(lds + PG8_SB(b, h) + boff + n * 2048 + k * 1024); } while (0)
; #define PG8_MMA(ai, bj, At, Bt) do { __builtin_amdgcn_s_setprio(1); _Pragma("unroll") for (int m = 0; m < 4; ++m) _Pragma("unroll") for (int n = 0; n < 2; ++n) _Pragma("unroll") for (int k = 0; k < 2; ++k) \
;         acc[ai][bj][m][n] = __builtin_amdgcn_mfma_f32_16x16x32_bf16(Bt[n][k], At[m][k], acc[ai][bj][m][n], 0, 0, 0); __builtin_amdgcn_s_setprio(0); } while (0)
; #define PG8_WAIT_V(n) asm volatile("s_waitcnt vmcnt(" #n ")" ::: "memory")
; #define PG8_WAIT_L(n) asm volatile("s_waitcnt lgkmcnt(" #n ")" ::: "memory")
; #define PG8_BAR __builtin_amdgcn_s_barrier()
; #define PG8_SCHED __builtin_amdgcn_sched_barrier(0)
; template <class Epi, class Sched, bool ALIGN_EPI = false, bool SP2 = false>
; __device__ __forceinline__ void gemm_phase(PG8_LAS unsigned char* lds, const Gemm g, const Sched& S, const Epi& E) {
;     ...
;             PG8_WAIT_V(8); PG8_WAIT_L(0); PG8_BAR; PG8_MMA(1, 0, At, B0); PG8_MMA(1, 1, At, B1); PG8_BAR; PG8_SCHED;
;             PG8_LDB(B0, 1, 0); PG8_LDB(B1, 1, 1); PG8_SCHED; PG8_LDA(At, 1, 0); PG8_STAGE(PG8_SA(0, 1), a2 + hstep, voffA);
;             PG8_WAIT_V(8); PG8_WAIT_L(0); PG8_BAR; PG8_MMA(0, 0, At, B0); PG8_MMA(0, 1, At, B1); PG8_BAR; PG8_SCHED;
	v_mfma_f32_16x16x32_bf16 v[62:65], v[146:149], v[200:203], v[62:65]
	v_mfma_f32_16x16x32_bf16 v[58:61], v[168:171], v[200:203], v[58:61]
	v_mfma_f32_16x16x32_bf16 v[42:45], v[168:171], v[208:211], v[42:45]
	v_mfma_f32_16x16x32_bf16 v[46:49], v[146:149], v[208:211], v[46:49]
	v_mfma_f32_16x16x32_bf16 v[30:33], v[146:149], v[216:219], v[30:33]
	v_mfma_f32_16x16x32_bf16 v[26:29], v[168:171], v[216:219], v[26:29]
	v_mfma_f32_16x16x32_bf16 v[10:13], v[168:171], v[224:227], v[10:13]
	v_mfma_f32_16x16x32_bf16 v[14:17], v[146:149], v[224:227], v[14:17]
	v_mfma_f32_16x16x32_bf16 v[62:65], v[158:161], v[204:207], v[62:65]
	v_mfma_f32_16x16x32_bf16 v[58:61], v[172:175], v[204:207], v[58:61]
	v_mfma_f32_16x16x32_bf16 v[42:45], v[172:175], v[212:215], v[42:45]
	v_mfma_f32_16x16x32_bf16 v[46:49], v[158:161], v[212:215], v[46:49]
	v_mfma_f32_16x16x32_bf16 v[30:33], v[158:161], v[220:223], v[30:33]
	v_mfma_f32_16x16x32_bf16 v[26:29], v[172:175], v[220:223], v[26:29]
	v_mfma_f32_16x16x32_bf16 v[10:13], v[172:175], v[228:231], v[10:13]
	v_mfma_f32_16x16x32_bf16 v[14:17], v[158:161], v[228:231], v[14:17]
	s_setprio 0
	s_setprio 1
	v_mfma_f32_16x16x32_bf16 v[54:57], v[176:179], v[200:203], v[54:57]
	v_mfma_f32_16x16x32_bf16 v[50:53], v[184:187], v[200:203], v[50:53]
	v_mfma_f32_16x16x32_bf16 v[34:37], v[184:187], v[208:211], v[34:37]
	v_mfma_f32_16x16x32_bf16 v[38:41], v[176:179], v[208:211], v[38:41]
	v_mfma_f32_16x16x32_bf16 v[22:25], v[176:179], v[216:219], v[22:25]
	v_mfma_f32_16x16x32_bf16 v[18:21], v[184:187], v[216:219], v[18:21]
	v_mfma_f32_16x16x32_bf16 v[2:5], v[184:187], v[224:227], v[2:5]
	v_mfma_f32_16x16x32_bf16 v[6:9], v[176:179], v[224:227], v[6:9]
	v_mfma_f32_16x16x32_bf16 v[54:57], v[180:183], v[204:207], v[54:57]
	v_mfma_f32_16x16x32_bf16 v[50:53], v[188:191], v[204:207], v[50:53]
	v_mfma_f32_16x16x32_bf16 v[34:37], v[188:191], v[212:215], v[34:37]
	v_mfma_f32_16x16x32_bf16 v[38:41], v[180:183], v[212:215], v[38:41]
	v_mfma_f32_16x16x32_bf16 v[22:25], v[180:183], v[220:223], v[22:25]
	v_mfma_f32_16x16x32_bf16 v[18:21], v[188:191], v[220:223], v[18:21]
	v_mfma_f32_16x16x32_bf16 v[2:5], v[188:191], v[228:231], v[2:5]
	v_mfma_f32_16x16x32_bf16 v[6:9], v[180:183], v[228:231], v[6:9]
	s_barrier
	s_setprio 0
	s_add_i32 s74, 0, 0x18000
	v_add_u32_e32 v166, s74, v153
	s_add_i32 s75, 0, 0x1c000
	ds_read_b128 v[146:149], v166
	ds_read_b128 v[158:161], v166 offset:1024
	ds_read_b128 v[168:171], v166 offset:2048
	ds_read_b128 v[172:175], v166 offset:3072
	v_add_u32_e32 v166, s75, v153
	ds_read_b128 v[176:179], v166
	ds_read_b128 v[180:183], v166 offset:1024
	ds_read_b128 v[184:187], v166 offset:2048
	ds_read_b128 v[188:191], v166 offset:3072
	s_add_u32 s70, s70, 0x80000
	s_addc_u32 s71, s71, 0
	s_mov_b32 m0, s27
	v_lshl_add_u64 v[240:241], s[70:71], 0, v[136:137]
	ds_read_b128 v[200:203], v157 offset:32768
	ds_read_b128 v[204:207], v157 offset:33792
	ds_read_b128 v[208:211], v157 offset:34816
	ds_read_b128 v[212:215], v157 offset:35840
	ds_read_b128 v[216:219], v157 offset:36864
	ds_read_b128 v[220:223], v157 offset:37888
	ds_read_b128 v[224:227], v157 offset:38912
	ds_read_b128 v[228:231], v157 offset:39936
	global_load_lds_dwordx4 v[240:241], off
	v_lshl_add_u64 v[240:241], s[70:71], 0, v[132:133]
	s_mov_b32 m0, s28
	s_nop 0
	global_load_lds_dwordx4 v[240:241], off
	s_waitcnt vmcnt(8)
	s_waitcnt lgkmcnt(0)
	s_setprio 1
	s_barrier
	v_mfma_f32_16x16x32_bf16 v[126:129], v[146:149], v[200:203], v[126:129]
	v_mfma_f32_16x16x32_bf16 v[122:125], v[168:171], v[200:203], v[122:125]
	v_mfma_f32_16x16x32_bf16 v[106:109], v[168:171], v[208:211], v[106:109]
	v_mfma_f32_16x16x32_bf16 v[110:113], v[146:149], v[208:211], v[110:113]
	v_mfma_f32_16x16x32_bf16 v[94:97], v[146:149], v[216:219], v[94:97]
	v_mfma_f32_16x16x32_bf16 v[90:93], v[168:171], v[216:219], v[90:93]
	v_mfma_f32_16x16x32_bf16 v[74:77], v[168:171], v[224:227], v[74:77]
	v_mfma_f32_16x16x32_bf16 v[78:81], v[146:149], v[224:227], v[78:81]
	v_mfma_f32_16x16x32_bf16 v[126:129], v[158:161], v[204:207], v[126:129]
	v_mfma_f32_16x16x32_bf16 v[122:125], v[172:175], v[204:207], v[122:125]
	v_mfma_f32_16x16x32_bf16 v[106:109], v[172:175], v[212:215], v[106:109]
	v_mfma_f32_16x16x32_bf16 v[110:113], v[158:161], v[212:215], v[110:113]
	v_mfma_f32_16x16x32_bf16 v[94:97], v[158:161], v[220:223], v[94:97]
	v_mfma_f32_16x16x32_bf16 v[90:93], v[172:175], v[220:223], v[90:93]
	v_mfma_f32_16x16x32_bf16 v[74:77], v[172:175], v[228:231], v[74:77]
	v_mfma_f32_16x16x32_bf16 v[78:81], v[158:161], v[228:231], v[78:81]
	s_setprio 0
	s_setprio 1
	v_mfma_f32_16x16x32_bf16 v[118:121], v[176:179], v[200:203], v[118:121]
	v_mfma_f32_16x16x32_bf16 v[114:117], v[184:187], v[200:203], v[114:117]
	v_mfma_f32_16x16x32_bf16 v[98:101], v[184:187], v[208:211], v[98:101]
	v_mfma_f32_16x16x32_bf16 v[102:105], v[176:179], v[208:211], v[102:105]
	v_mfma_f32_16x16x32_bf16 v[86:89], v[176:179], v[216:219], v[86:89]
	v_mfma_f32_16x16x32_bf16 v[82:85], v[184:187], v[216:219], v[82:85]
	v_mfma_f32_16x16x32_bf16 v[66:69], v[184:187], v[224:227], v[66:69]
	v_mfma_f32_16x16x32_bf16 v[70:73], v[176:179], v[224:227], v[70:73]
	v_mfma_f32_16x16x32_bf16 v[118:121], v[180:183], v[204:207], v[118:121]
	v_mfma_f32_16x16x32_bf16 v[114:117], v[188:191], v[204:207], v[114:117]
	v_mfma_f32_16x16x32_bf16 v[98:101], v[188:191], v[212:215], v[98:101]
	v_mfma_f32_16x16x32_bf16 v[102:105], v[180:183], v[212:215], v[102:105]
	v_mfma_f32_16x16x32_bf16 v[86:89], v[180:183], v[220:223], v[86:89]
	v_mfma_f32_16x16x32_bf16 v[82:85], v[188:191], v[220:223], v[82:85]
	v_mfma_f32_16x16x32_bf16 v[66:69], v[188:191], v[228:231], v[66:69]
	v_mfma_f32_16x16x32_bf16 v[70:73], v[180:183], v[228:231], v[70:73]
	s_barrier
; #define PG8_STAGE(bufoff, gbase, voff) do { _Pragma("unroll") for (int _i = 0; _i < 2; ++_i) \
;         __builtin_amdgcn_global_load_lds((const unsigned*)((const char*)(gbase) + (voff)[_i]), (PG8_LAS unsigned*)(lds + (bufoff) + ldsw + _i * 8192), 16, 0, 0); } while (0)
; #define PG8_LDA(dst, b, h) do { _Pragma("unroll") for (int m = 0; m < 4; ++m) _Pragma("unroll") for (int k = 0; k < 2; ++k) dst[m][k] = *(const PG8_LAS bf16x8*)(lds + PG8_SA(b, h) + aoff + m * 2048 + k * 1024); } while (0)
; #define PG8_MMA(ai, bj, At, Bt) do { __builtin_amdgcn_s_setprio(1); _Pragma("unroll") for (int m = 0; m < 4; ++m) _Pragma("unroll") for (int n = 0; n < 2; ++n) _Pragma("unroll") for (int k = 0; k < 2; ++k) \
;         acc[ai][bj][m][n] = __builtin_amdgcn_mfma_f32_16x16x32_bf16(Bt[n][k], At[m][k], acc[ai][bj][m][n], 0, 0, 0); __builtin_amdgcn_s_setprio(0); } while (0)
; #define PG8_WAIT_V(n) asm volatile("s_waitcnt vmcnt(" #n ")" ::: "memory")
; #define PG8_WAIT_L(n) asm volatile("s_waitcnt lgkmcnt(" #n ")" ::: "memory")
; #define PG8_BAR __builtin_amdgcn_s_barrier()
; #define PG8_SCHED __builtin_amdgcn_sched_barrier(0)
; template <class Epi, class Sched, bool ALIGN_EPI = false, bool SP2 = false>
; __device__ __forceinline__ void gemm_phase(PG8_LAS unsigned char* lds, const Gemm g, const Sched& S, const Epi& E) {
;     ...
;         for (int t = 0; t < nt; t += 2) {
;             const bool last = (t == nt - 2);
;             const char* a1 = cA + (size_t)(t + 1) * kstep;
;             const char* a2 = last ? nA : cA + (size_t)(t + 2) * kstep; const char* b2 = last ? nB : cB + (size_t)(t + 2) * kstep;
;     ...
;             PG8_LDA(At, 1, 1); PG8_STAGE(PG8_SB(1, 0), b3, voffB); PG8_STAGE(PG8_SB(1, 1), b3 + hstep, voffB); PG8_STAGE(PG8_SA(1, 0), a3, voffA);
;             PG8_WAIT_V(8); PG8_WAIT_L(0); PG8_BAR; PG8_MMA(1, 0, At, B0); PG8_MMA(1, 1, At, B1); PG8_BAR; PG8_SCHED;
	s_setprio 0
	s_add_i32 s70, s74, s2
	v_lshl_add_u64 v[150:151], v[150:151], 0, s[8:9]
	s_mov_b32 m0, s70
	ds_read_b128 v[200:203], v157 offset:49152
	ds_read_b128 v[204:207], v157 offset:50176
	ds_read_b128 v[208:211], v157 offset:51200
	ds_read_b128 v[212:215], v157 offset:52224
	ds_read_b128 v[216:219], v157 offset:53248
	ds_read_b128 v[220:223], v157 offset:54272
	ds_read_b128 v[224:227], v157 offset:55296
	ds_read_b128 v[228:231], v157 offset:56320
	global_load_lds_dwordx4 v[150:151], off
	s_add_i32 m0, s70, 0x2000
	s_add_u32 s68, s68, 0x80080
	v_lshl_add_u64 v[150:151], v[162:163], 0, s[8:9]
	s_addc_u32 s69, s69, 0
	s_add_i32 s70, s75, s2
	global_load_lds_dwordx4 v[150:151], off
	v_lshl_add_u64 v[150:151], s[68:69], 0, v[134:135]
	s_mov_b32 m0, s70
	s_nop 0
	global_load_lds_dwordx4 v[150:151], off
	v_lshl_add_u64 v[150:151], s[68:69], 0, v[130:131]
	s_add_i32 m0, s70, 0x2000
	s_nop 0
	global_load_lds_dwordx4 v[150:151], off
	v_lshl_add_u64 v[150:151], v[192:193], 0, s[8:9]
	s_mov_b32 m0, s30
	s_nop 0
	global_load_lds_dwordx4 v[150:151], off
	v_lshl_add_u64 v[150:151], v[232:233], 0, s[8:9]
	s_mov_b32 m0, s33
	s_nop 0
	global_load_lds_dwordx4 v[150:151], off
	s_waitcnt vmcnt(8)
	s_waitcnt lgkmcnt(0)
	s_setprio 1
	s_barrier
	v_mfma_f32_16x16x32_bf16 v[62:65], v[146:149], v[200:203], v[62:65]
	v_mfma_f32_16x16x32_bf16 v[58:61], v[168:171], v[200:203], v[58:61]
	v_mfma_f32_16x16x32_bf16 v[42:45], v[168:171], v[208:211], v[42:45]
	v_mfma_f32_16x16x32_bf16 v[46:49], v[146:149], v[208:211], v[46:49]
	v_mfma_f32_16x16x32_bf16 v[30:33], v[146:149], v[216:219], v[30:33]
	v_mfma_f32_16x16x32_bf16 v[26:29], v[168:171], v[216:219], v[26:29]
	v_mfma_f32_16x16x32_bf16 v[10:13], v[168:171], v[224:227], v[10:13]
	v_mfma_f32_16x16x32_bf16 v[14:17], v[146:149], v[224:227], v[14:17]
	v_mfma_f32_16x16x32_bf16 v[62:65], v[158:161], v[204:207], v[62:65]
	v_mfma_f32_16x16x32_bf16 v[58:61], v[172:175], v[204:207], v[58:61]
	v_mfma_f32_16x16x32_bf16 v[42:45], v[172:175], v[212:215], v[42:45]
	v_mfma_f32_16x16x32_bf16 v[46:49], v[158:161], v[212:215], v[46:49]
	v_mfma_f32_16x16x32_bf16 v[30:33], v[158:161], v[220:223], v[30:33]
	v_mfma_f32_16x16x32_bf16 v[26:29], v[172:175], v[220:223], v[26:29]
	v_mfma_f32_16x16x32_bf16 v[10:13], v[172:175], v[228:231], v[10:13]
	v_mfma_f32_16x16x32_bf16 v[14:17], v[158:161], v[228:231], v[14:17]
	s_setprio 0
	s_setprio 1
	v_mfma_f32_16x16x32_bf16 v[54:57], v[176:179], v[200:203], v[54:57]
	v_mfma_f32_16x16x32_bf16 v[50:53], v[184:187], v[200:203], v[50:53]
	v_mfma_f32_16x16x32_bf16 v[34:37], v[184:187], v[208:211], v[34:37]
	v_mfma_f32_16x16x32_bf16 v[38:41], v[176:179], v[208:211], v[38:41]
	v_mfma_f32_16x16x32_bf16 v[22:25], v[176:179], v[216:219], v[22:25]
	v_mfma_f32_16x16x32_bf16 v[18:21], v[184:187], v[216:219], v[18:21]
	v_mfma_f32_16x16x32_bf16 v[2:5], v[184:187], v[224:227], v[2:5]
	v_mfma_f32_16x16x32_bf16 v[6:9], v[176:179], v[224:227], v[6:9]
	v_mfma_f32_16x16x32_bf16 v[54:57], v[180:183], v[204:207], v[54:57]
	v_mfma_f32_16x16x32_bf16 v[50:53], v[188:191], v[204:207], v[50:53]
	v_mfma_f32_16x16x32_bf16 v[34:37], v[188:191], v[212:215], v[34:37]
	v_mfma_f32_16x16x32_bf16 v[38:41], v[180:183], v[212:215], v[38:41]
	v_mfma_f32_16x16x32_bf16 v[22:25], v[180:183], v[220:223], v[22:25]
	v_mfma_f32_16x16x32_bf16 v[18:21], v[188:191], v[220:223], v[18:21]
	v_mfma_f32_16x16x32_bf16 v[2:5], v[188:191], v[228:231], v[2:5]
	v_mfma_f32_16x16x32_bf16 v[6:9], v[180:183], v[228:231], v[6:9]
	s_barrier
	s_setprio 0
	s_add_i32 s73, s73, 2
	s_add_u32 s66, s66, 0x100
	s_addc_u32 s67, s67, 0
	s_add_u32 s65, s65, 0x100
	s_addc_u32 s72, s72, 0
	s_cmp_gt_u32 s73, 29
	s_cbranch_scc0 .LBB0_1078
	s_and_b64 vcc, exec, s[10:11]
	s_cbranch_vccz .LBB0_1081
	s_barrier

; #define PG8_STAGE(bufoff, gbase, voff) do { _Pragma("unroll") for (int _i = 0; _i < 2; ++_i) \
;         __builtin_amdgcn_global_load_lds((const unsigned*)((const char*)(gbase) + (voff)[_i]), (PG8_LAS unsigned*)(lds + (bufoff) + ldsw + _i * 8192), 16, 0, 0); } while (0)
; #define PG8_LDA(dst, b, h) do { _Pragma("unroll") for (int m = 0; m < 4; ++m) _Pragma("unroll") for (int k = 0; k < 2; ++k) dst[m][k] = *(const PG8_LAS bf16x8*)(lds + PG8_SA(b, h) + aoff + m * 2048 + k * 1024); } while (0)
; #define PG8_LDB(dst, b, h) do { _Pragma("unroll") for (int n = 0; n < 2; ++n) _Pragma("unroll") for (int k = 0; k < 2; ++k) dst[n][k] = *(const PG8_LAS bf16x8*)(lds + PG8_SB(b, h) + boff + n * 2048 + k * 1024); } while (0)
; #define PG8_MMA(ai, bj, At, Bt) do { __builtin_amdgcn_s_setprio(1); _Pragma("unroll") for (int m = 0; m < 4; ++m) _Pragma("unroll") for (int n = 0; n < 2; ++n) _Pragma("unroll") for (int k = 0; k < 2; ++k) \
;         acc[ai][bj][m][n] = __builtin_amdgcn_mfma_f32_16x16x32_bf16(Bt[n][k], At[m][k], acc[ai][bj][m][n], 0, 0, 0); __builtin_amdgcn_s_setprio(0); } while (0)
; #define PG8_WAIT_V(n) asm volatile("s_waitcnt vmcnt(" #n ")" ::: "memory")
; #define PG8_WAIT_L(n) asm volatile("s_waitcnt lgkmcnt(" #n ")" ::: "memory")
; template <class Epi, class Sched, bool ALIGN_EPI = false, bool SP2 = false>
; __device__ __forceinline__ void gemm_phase(PG8_LAS unsigned char* lds, const Gemm g, const Sched& S, const Epi& E) {
;     ...
;             const bool last = (t == nt - 2);
;             const char* a1 = cA + (size_t)(t + 1) * kstep;
;             const char* a2 = last ? nA : cA + (size_t)(t + 2) * kstep; const char* b2 = last ? nB : cB + (size_t)(t + 2) * kstep;
;             const char* a3 = a2 + kstep; const char* b3 = b2 + kstep;
;             if (last && has_next) S.a_ready(nxt);
;             if constexpr (SP2) {
;             PG8_LDB(B0, 0, 0); PG8_LDB(B1, 0, 1); PG8_SCHED; PG8_LDA(At, 0, 0); PG8_STAGE(PG8_SA(1, 1), a1 + hstep, voffA);
;             PG8_WAIT_V(8); PG8_WAIT_L(0); PG8_BAR; PG8_MMA(0, 0, At, B0); PG8_MMA(0, 1, At, B1); PG8_BAR; PG8_SCHED;
;             PG8_LDA(At, 0, 1); PG8_STAGE(PG8_SB(0, 0), b2, voffB); PG8_STAGE(PG8_SB(0, 1), b2 + hstep, voffB); PG8_STAGE(PG8_SA(0, 0), a2, voffA);
;             PG8_WAIT_V(8); PG8_WAIT_L(0); PG8_BAR; PG8_MMA(1, 0, At, B0); PG8_MMA(1, 1, At, B1); PG8_BAR; PG8_SCHED;
.LBB0_1203:
	ds_read_b128 v[146:149], v171
	ds_read_b128 v[176:179], v171 offset:1024
	ds_read_b128 v[180:183], v171 offset:2048
	ds_read_b128 v[184:187], v171 offset:3072
	ds_read_b128 v[188:191], v172
	ds_read_b128 v[200:203], v172 offset:1024
	ds_read_b128 v[204:207], v172 offset:2048
	ds_read_b128 v[208:211], v172 offset:3072
	s_add_u32 s63, s64, 0xfff00080
	s_addc_u32 s66, s65, -1
	s_cmp_eq_u32 s61, 60
	s_cselect_b32 s69, s34, s66
	s_cselect_b32 s68, s35, s63
	s_cselect_b32 s67, s40, s55
	s_cselect_b32 s66, s41, s53
	v_lshl_add_u64 v[150:151], s[64:65], 0, v[138:139]
	s_add_i32 m0, s4, 0xc000
	ds_read_b128 v[212:215], v173
	ds_read_b128 v[216:219], v173 offset:1024
	ds_read_b128 v[220:223], v173 offset:2048
	ds_read_b128 v[224:227], v173 offset:3072
	ds_read_b128 v[228:231], v173 offset:4096
	ds_read_b128 v[240:243], v173 offset:5120
	ds_read_b128 v[244:247], v173 offset:6144
	ds_read_b128 v[248:251], v173 offset:7168
	global_load_lds_dwordx4 v[150:151], off
	v_lshl_add_u64 v[150:151], s[64:65], 0, v[140:141]
	s_add_i32 m0, s4, 0xe000
	s_nop 0
	global_load_lds_dwordx4 v[150:151], off
	s_waitcnt vmcnt(8)
	s_waitcnt lgkmcnt(0)
	s_setprio 1
	s_barrier
	v_mfma_f32_16x16x32_bf16 v[126:129], v[146:149], v[212:215], v[126:129]
	v_mfma_f32_16x16x32_bf16 v[122:125], v[180:183], v[212:215], v[122:125]
	v_mfma_f32_16x16x32_bf16 v[106:109], v[180:183], v[220:223], v[106:109]
	v_mfma_f32_16x16x32_bf16 v[110:113], v[146:149], v[220:223], v[110:113]
	v_mfma_f32_16x16x32_bf16 v[94:97], v[146:149], v[228:231], v[94:97]
	v_mfma_f32_16x16x32_bf16 v[90:93], v[180:183], v[228:231], v[90:93]
	v_mfma_f32_16x16x32_bf16 v[74:77], v[180:183], v[244:247], v[74:77]
	v_mfma_f32_16x16x32_bf16 v[78:81], v[146:149], v[244:247], v[78:81]
	v_mfma_f32_16x16x32_bf16 v[126:129], v[176:179], v[216:219], v[126:129]
	v_mfma_f32_16x16x32_bf16 v[122:125], v[184:187], v[216:219], v[122:125]
	v_mfma_f32_16x16x32_bf16 v[106:109], v[184:187], v[224:227], v[106:109]
	v_mfma_f32_16x16x32_bf16 v[110:113], v[176:179], v[224:227], v[110:113]
	v_mfma_f32_16x16x32_bf16 v[94:97], v[176:179], v[240:243], v[94:97]
	v_mfma_f32_16x16x32_bf16 v[90:93], v[184:187], v[240:243], v[90:93]
	v_mfma_f32_16x16x32_bf16 v[74:77], v[184:187], v[248:251], v[74:77]
	v_mfma_f32_16x16x32_bf16 v[78:81], v[176:179], v[248:251], v[78:81]
	s_setprio 0
	s_setprio 1
	v_mfma_f32_16x16x32_bf16 v[118:121], v[188:191], v[212:215], v[118:121]
	v_mfma_f32_16x16x32_bf16 v[114:117], v[204:207], v[212:215], v[114:117]
	v_mfma_f32_16x16x32_bf16 v[98:101], v[204:207], v[220:223], v[98:101]
	v_mfma_f32_16x16x32_bf16 v[102:105], v[188:191], v[220:223], v[102:105]
	v_mfma_f32_16x16x32_bf16 v[86:89], v[188:191], v[228:231], v[86:89]
	v_mfma_f32_16x16x32_bf16 v[82:85], v[204:207], v[228:231], v[82:85]
	v_mfma_f32_16x16x32_bf16 v[66:69], v[204:207], v[244:247], v[66:69]
	v_mfma_f32_16x16x32_bf16 v[70:73], v[188:191], v[244:247], v[70:73]
	v_mfma_f32_16x16x32_bf16 v[118:121], v[200:203], v[216:219], v[118:121]
	v_mfma_f32_16x16x32_bf16 v[114:117], v[208:211], v[216:219], v[114:117]
	v_mfma_f32_16x16x32_bf16 v[98:101], v[208:211], v[224:227], v[98:101]
	v_mfma_f32_16x16x32_bf16 v[102:105], v[200:203], v[224:227], v[102:105]
	v_mfma_f32_16x16x32_bf16 v[86:89], v[200:203], v[240:243], v[86:89]
	v_mfma_f32_16x16x32_bf16 v[82:85], v[208:211], v[240:243], v[82:85]
	v_mfma_f32_16x16x32_bf16 v[66:69], v[208:211], v[248:251], v[66:69]
	v_mfma_f32_16x16x32_bf16 v[70:73], v[200:203], v[248:251], v[70:73]
	s_barrier
	s_setprio 0
	s_add_i32 s63, s31, s2
	v_lshl_add_u64 v[150:151], s[66:67], 0, v[132:133]
	s_mov_b32 m0, s63
	ds_read_b128 v[212:215], v173 offset:16384
	ds_read_b128 v[216:219], v173 offset:17408
	ds_read_b128 v[220:223], v173 offset:18432
	ds_read_b128 v[224:227], v173 offset:19456
	ds_read_b128 v[228:231], v173 offset:20480
	ds_read_b128 v[240:243], v173 offset:21504
	ds_read_b128 v[244:247], v173 offset:22528
	ds_read_b128 v[248:251], v173 offset:23552
	global_load_lds_dwordx4 v[150:151], off
	s_add_i32 m0, s63, 0x2000
	s_add_u32 s70, s66, 0x100000
	v_lshl_add_u64 v[192:193], s[66:67], 0, v[136:137]
	s_addc_u32 s71, s67, 0
	s_add_i32 s63, s39, s2
	global_load_lds_dwordx4 v[192:193], off
	v_lshl_add_u64 v[232:233], s[70:71], 0, v[132:133]
	s_mov_b32 m0, s63
	v_lshl_add_u64 v[252:253], s[68:69], 0, v[134:135]
	global_load_lds_dwordx4 v[232:233], off
	v_lshl_add_u64 v[232:233], s[70:71], 0, v[136:137]
	s_add_i32 m0, s63, 0x2000
	s_nop 0
	global_load_lds_dwordx4 v[232:233], off
	v_lshl_add_u64 v[232:233], s[68:69], 0, v[130:131]
	s_mov_b32 m0, s4
	s_nop 0
	global_load_lds_dwordx4 v[232:233], off
	s_mov_b32 m0, s5
	s_nop 0
	global_load_lds_dwordx4 v[252:253], off
	s_waitcnt vmcnt(8)
	s_waitcnt lgkmcnt(0)
	s_setprio 1
	s_barrier
; #define PG8_STAGE(bufoff, gbase, voff) do { _Pragma("unroll") for (int _i = 0; _i < 2; ++_i) \
;         __builtin_amdgcn_global_load_lds((const unsigned*)((const char*)(gbase) + (voff)[_i]), (PG8_LAS unsigned*)(lds + (bufoff) + ldsw + _i * 8192), 16, 0, 0); } while (0)
; #define PG8_LDA(dst, b, h) do { _Pragma("unroll") for (int m = 0; m < 4; ++m) _Pragma("unroll") for (int k = 0; k < 2; ++k) dst[m][k] = *(const PG8_LAS bf16x8*)(lds + PG8_SA(b, h) + aoff + m * 2048 + k * 1024); } while (0)
; #define PG8_LDB(dst, b, h) do { _Pragma("unroll") for (int n = 0; n < 2; ++n) _Pragma("unroll") for (int k = 0; k < 2; ++k) dst[n][k] = *(const PG8_LAS bf16x8*)(lds + PG8_SB(b, h) + boff + n * 2048 + k * 1024); } while (0)
; #define PG8_MMA(ai, bj, At, Bt) do { __builtin_amdgcn_s_setprio(1); _Pragma("unroll") for (int m = 0; m < 4; ++m) _Pragma("unroll") for (int n = 0; n < 2; ++n) _Pragma("unroll") for (int k = 0; k < 2; ++k) \
;         acc[ai][bj][m][n] = __builtin_amdgcn_mfma_f32_16x16x32_bf16(Bt[n][k], At[m][k], acc[ai][bj][m][n], 0, 0, 0); __builtin_amdgcn_s_setprio(0); } while (0)
; #define PG8_WAIT_V(n) asm volatile("s_waitcnt vmcnt(" #n ")" ::: "memory")
; #define PG8_WAIT_L(n) asm volatile("s_waitcnt lgkmcnt(" #n ")" ::: "memory")
; #define PG8_BAR __builtin_amdgcn_s_barrier()
; #define PG8_SCHED __builtin_amdgcn_sched_barrier(0)
; template <class Epi, class Sched, bool ALIGN_EPI = false, bool SP2 = false>
; __device__ __forceinline__ void gemm_phase(PG8_LAS unsigned char* lds, const Gemm g, const Sched& S, const Epi& E) {
;     ...
;             PG8_WAIT_V(8); PG8_WAIT_L(0); PG8_BAR; PG8_MMA(1, 0, At, B0); PG8_MMA(1, 1, At, B1); PG8_BAR; PG8_SCHED;
;             PG8_LDB(B0, 1, 0); PG8_LDB(B1, 1, 1); PG8_SCHED; PG8_LDA(At, 1, 0); PG8_STAGE(PG8_SA(0, 1), a2 + hstep, voffA);
;             PG8_WAIT_V(8); PG8_WAIT_L(0); PG8_BAR; PG8_MMA(0, 0, At, B0); PG8_MMA(0, 1, At, B1); PG8_BAR; PG8_SCHED;
	v_mfma_f32_16x16x32_bf16 v[62:65], v[146:149], v[212:215], v[62:65]
	v_mfma_f32_16x16x32_bf16 v[58:61], v[180:183], v[212:215], v[58:61]
	v_mfma_f32_16x16x32_bf16 v[42:45], v[180:183], v[220:223], v[42:45]
	v_mfma_f32_16x16x32_bf16 v[46:49], v[146:149], v[220:223], v[46:49]
	v_mfma_f32_16x16x32_bf16 v[30:33], v[146:149], v[228:231], v[30:33]
	v_mfma_f32_16x16x32_bf16 v[26:29], v[180:183], v[228:231], v[26:29]
	v_mfma_f32_16x16x32_bf16 v[10:13], v[180:183], v[244:247], v[10:13]
	v_mfma_f32_16x16x32_bf16 v[14:17], v[146:149], v[244:247], v[14:17]
	v_mfma_f32_16x16x32_bf16 v[62:65], v[176:179], v[216:219], v[62:65]
	v_mfma_f32_16x16x32_bf16 v[58:61], v[184:187], v[216:219], v[58:61]
	v_mfma_f32_16x16x32_bf16 v[42:45], v[184:187], v[224:227], v[42:45]
	v_mfma_f32_16x16x32_bf16 v[46:49], v[176:179], v[224:227], v[46:49]
	v_mfma_f32_16x16x32_bf16 v[30:33], v[176:179], v[240:243], v[30:33]
	v_mfma_f32_16x16x32_bf16 v[26:29], v[184:187], v[240:243], v[26:29]
	v_mfma_f32_16x16x32_bf16 v[10:13], v[184:187], v[248:251], v[10:13]
	v_mfma_f32_16x16x32_bf16 v[14:17], v[176:179], v[248:251], v[14:17]
	s_setprio 0
	s_setprio 1
	v_mfma_f32_16x16x32_bf16 v[54:57], v[188:191], v[212:215], v[54:57]
	v_mfma_f32_16x16x32_bf16 v[50:53], v[204:207], v[212:215], v[50:53]
	v_mfma_f32_16x16x32_bf16 v[34:37], v[204:207], v[220:223], v[34:37]
	v_mfma_f32_16x16x32_bf16 v[38:41], v[188:191], v[220:223], v[38:41]
	v_mfma_f32_16x16x32_bf16 v[22:25], v[188:191], v[228:231], v[22:25]
	v_mfma_f32_16x16x32_bf16 v[18:21], v[204:207], v[228:231], v[18:21]
	v_mfma_f32_16x16x32_bf16 v[2:5], v[204:207], v[244:247], v[2:5]
	v_mfma_f32_16x16x32_bf16 v[6:9], v[188:191], v[244:247], v[6:9]
	v_mfma_f32_16x16x32_bf16 v[54:57], v[200:203], v[216:219], v[54:57]
	v_mfma_f32_16x16x32_bf16 v[50:53], v[208:211], v[216:219], v[50:53]
	v_mfma_f32_16x16x32_bf16 v[34:37], v[208:211], v[224:227], v[34:37]
	v_mfma_f32_16x16x32_bf16 v[38:41], v[200:203], v[224:227], v[38:41]
	v_mfma_f32_16x16x32_bf16 v[22:25], v[200:203], v[240:243], v[22:25]
	v_mfma_f32_16x16x32_bf16 v[18:21], v[208:211], v[240:243], v[18:21]
	v_mfma_f32_16x16x32_bf16 v[2:5], v[208:211], v[248:251], v[2:5]
	v_mfma_f32_16x16x32_bf16 v[6:9], v[200:203], v[248:251], v[6:9]
	s_barrier
	s_setprio 0
	s_add_i32 s63, 0, 0x18000
	v_add_u32_e32 v175, s63, v153
	s_add_i32 s70, 0, 0x1c000
	ds_read_b128 v[146:149], v175
	ds_read_b128 v[176:179], v175 offset:1024
	ds_read_b128 v[180:183], v175 offset:2048
	ds_read_b128 v[184:187], v175 offset:3072
	v_add_u32_e32 v175, s70, v153
	ds_read_b128 v[188:191], v175
	ds_read_b128 v[200:203], v175 offset:1024
	ds_read_b128 v[204:207], v175 offset:2048
	ds_read_b128 v[208:211], v175 offset:3072
	s_add_u32 s68, s68, 0x100000
	s_addc_u32 s69, s69, 0
	s_mov_b32 m0, s16
	v_lshl_add_u64 v[194:195], s[68:69], 0, v[130:131]
	ds_read_b128 v[212:215], v173 offset:32768
	ds_read_b128 v[216:219], v173 offset:33792
	ds_read_b128 v[220:223], v173 offset:34816
	ds_read_b128 v[224:227], v173 offset:35840
	ds_read_b128 v[228:231], v173 offset:36864
	ds_read_b128 v[240:243], v173 offset:37888
	ds_read_b128 v[244:247], v173 offset:38912
	ds_read_b128 v[248:251], v173 offset:39936
	global_load_lds_dwordx4 v[194:195], off
	v_lshl_add_u64 v[194:195], s[68:69], 0, v[134:135]
	s_mov_b32 m0, s17
	s_nop 0
	global_load_lds_dwordx4 v[194:195], off
	s_waitcnt vmcnt(8)
	s_waitcnt lgkmcnt(0)
	s_setprio 1
	s_barrier
	v_mfma_f32_16x16x32_bf16 v[126:129], v[146:149], v[212:215], v[126:129]
	v_mfma_f32_16x16x32_bf16 v[122:125], v[180:183], v[212:215], v[122:125]
	v_mfma_f32_16x16x32_bf16 v[106:109], v[180:183], v[220:223], v[106:109]
	v_mfma_f32_16x16x32_bf16 v[110:113], v[146:149], v[220:223], v[110:113]
	v_mfma_f32_16x16x32_bf16 v[94:97], v[146:149], v[228:231], v[94:97]
	v_mfma_f32_16x16x32_bf16 v[90:93], v[180:183], v[228:231], v[90:93]
	v_mfma_f32_16x16x32_bf16 v[74:77], v[180:183], v[244:247], v[74:77]
	v_mfma_f32_16x16x32_bf16 v[78:81], v[146:149], v[244:247], v[78:81]
	v_mfma_f32_16x16x32_bf16 v[126:129], v[176:179], v[216:219], v[126:129]
	v_mfma_f32_16x16x32_bf16 v[122:125], v[184:187], v[216:219], v[122:125]
	v_mfma_f32_16x16x32_bf16 v[106:109], v[184:187], v[224:227], v[106:109]
	v_mfma_f32_16x16x32_bf16 v[110:113], v[176:179], v[224:227], v[110:113]
	v_mfma_f32_16x16x32_bf16 v[94:97], v[176:179], v[240:243], v[94:97]
	v_mfma_f32_16x16x32_bf16 v[90:93], v[184:187], v[240:243], v[90:93]
	v_mfma_f32_16x16x32_bf16 v[74:77], v[184:187], v[248:251], v[74:77]
	v_mfma_f32_16x16x32_bf16 v[78:81], v[176:179], v[248:251], v[78:81]
	s_setprio 0
	s_setprio 1
	v_mfma_f32_16x16x32_bf16 v[118:121], v[188:191], v[212:215], v[118:121]
	v_mfma_f32_16x16x32_bf16 v[114:117], v[204:207], v[212:215], v[114:117]
	v_mfma_f32_16x16x32_bf16 v[98:101], v[204:207], v[220:223], v[98:101]
	v_mfma_f32_16x16x32_bf16 v[102:105], v[188:191], v[220:223], v[102:105]
	v_mfma_f32_16x16x32_bf16 v[86:89], v[188:191], v[228:231], v[86:89]
	v_mfma_f32_16x16x32_bf16 v[82:85], v[204:207], v[228:231], v[82:85]
	v_mfma_f32_16x16x32_bf16 v[66:69], v[204:207], v[244:247], v[66:69]
	v_mfma_f32_16x16x32_bf16 v[70:73], v[188:191], v[244:247], v[70:73]
	v_mfma_f32_16x16x32_bf16 v[118:121], v[200:203], v[216:219], v[118:121]
	v_mfma_f32_16x16x32_bf16 v[114:117], v[208:211], v[216:219], v[114:117]
	v_mfma_f32_16x16x32_bf16 v[98:101], v[208:211], v[224:227], v[98:101]
	v_mfma_f32_16x16x32_bf16 v[102:105], v[200:203], v[224:227], v[102:105]
	v_mfma_f32_16x16x32_bf16 v[86:89], v[200:203], v[240:243], v[86:89]
	v_mfma_f32_16x16x32_bf16 v[82:85], v[208:211], v[240:243], v[82:85]
	v_mfma_f32_16x16x32_bf16 v[66:69], v[208:211], v[248:251], v[66:69]
	v_mfma_f32_16x16x32_bf16 v[70:73], v[200:203], v[248:251], v[70:73]
	s_barrier
; #define PG8_STAGE(bufoff, gbase, voff) do { _Pragma("unroll") for (int _i = 0; _i < 2; ++_i) \
;         __builtin_amdgcn_global_load_lds((const unsigned*)((const char*)(gbase) + (voff)[_i]), (PG8_LAS unsigned*)(lds + (bufoff) + ldsw + _i * 8192), 16, 0, 0); } while (0)
; #define PG8_LDA(dst, b, h) do { _Pragma("unroll") for (int m = 0; m < 4; ++m) _Pragma("unroll") for (int k = 0; k < 2; ++k) dst[m][k] = *(const PG8_LAS bf16x8*)(lds + PG8_SA(b, h) + aoff + m * 2048 + k * 1024); } while (0)
; #define PG8_MMA(ai, bj, At, Bt) do { __builtin_amdgcn_s_setprio(1); _Pragma("unroll") for (int m = 0; m < 4; ++m) _Pragma("unroll") for (int n = 0; n < 2; ++n) _Pragma("unroll") for (int k = 0; k < 2; ++k) \
;         acc[ai][bj][m][n] = __builtin_amdgcn_mfma_f32_16x16x32_bf16(Bt[n][k], At[m][k], acc[ai][bj][m][n], 0, 0, 0); __builtin_amdgcn_s_setprio(0); } while (0)
; #define PG8_WAIT_V(n) asm volatile("s_waitcnt vmcnt(" #n ")" ::: "memory")
; #define PG8_WAIT_L(n) asm volatile("s_waitcnt lgkmcnt(" #n ")" ::: "memory")
; #define PG8_BAR __builtin_amdgcn_s_barrier()
; #define PG8_SCHED __builtin_amdgcn_sched_barrier(0)
; template <class Epi, class Sched, bool ALIGN_EPI = false, bool SP2 = false>
; __device__ __forceinline__ void gemm_phase(PG8_LAS unsigned char* lds, const Gemm g, const Sched& S, const Epi& E) {
;     ...
;         for (int t = 0; t < nt; t += 2) {
;             const bool last = (t == nt - 2);
;             const char* a1 = cA + (size_t)(t + 1) * kstep;
;             const char* a2 = last ? nA : cA + (size_t)(t + 2) * kstep; const char* b2 = last ? nB : cB + (size_t)(t + 2) * kstep;
;     ...
;             PG8_LDA(At, 1, 1); PG8_STAGE(PG8_SB(1, 0), b3, voffB); PG8_STAGE(PG8_SB(1, 1), b3 + hstep, voffB); PG8_STAGE(PG8_SA(1, 0), a3, voffA);
;             PG8_WAIT_V(8); PG8_WAIT_L(0); PG8_BAR; PG8_MMA(1, 0, At, B0); PG8_MMA(1, 1, At, B1); PG8_BAR; PG8_SCHED;
	s_setprio 0
	s_add_i32 s63, s63, s2
	v_lshl_add_u64 v[150:151], v[150:151], 0, s[44:45]
	s_mov_b32 m0, s63
	ds_read_b128 v[212:215], v173 offset:49152
	ds_read_b128 v[216:219], v173 offset:50176
	ds_read_b128 v[220:223], v173 offset:51200
	ds_read_b128 v[224:227], v173 offset:52224
	ds_read_b128 v[228:231], v173 offset:53248
	ds_read_b128 v[240:243], v173 offset:54272
	ds_read_b128 v[244:247], v173 offset:55296
	ds_read_b128 v[248:251], v173 offset:56320
	global_load_lds_dwordx4 v[150:151], off
	s_add_i32 m0, s63, 0x2000
	s_add_u32 s66, s66, 0x100080
	v_lshl_add_u64 v[150:151], v[192:193], 0, s[44:45]
	s_addc_u32 s67, s67, 0
	s_add_i32 s63, s70, s2
	global_load_lds_dwordx4 v[150:151], off
	v_lshl_add_u64 v[150:151], s[66:67], 0, v[132:133]
	s_mov_b32 m0, s63
	s_nop 0
	global_load_lds_dwordx4 v[150:151], off
	v_lshl_add_u64 v[150:151], s[66:67], 0, v[136:137]
	s_add_i32 m0, s63, 0x2000
	s_nop 0
	global_load_lds_dwordx4 v[150:151], off
	v_lshl_add_u64 v[150:151], v[232:233], 0, s[44:45]
	s_mov_b32 m0, s26
	s_nop 0
	global_load_lds_dwordx4 v[150:151], off
	v_lshl_add_u64 v[150:151], v[252:253], 0, s[44:45]
	s_mov_b32 m0, s27
	s_nop 0
	global_load_lds_dwordx4 v[150:151], off
	s_waitcnt vmcnt(8)
	s_waitcnt lgkmcnt(0)
	s_setprio 1
	s_barrier
	v_mfma_f32_16x16x32_bf16 v[62:65], v[146:149], v[212:215], v[62:65]
	v_mfma_f32_16x16x32_bf16 v[58:61], v[180:183], v[212:215], v[58:61]
	v_mfma_f32_16x16x32_bf16 v[42:45], v[180:183], v[220:223], v[42:45]
	v_mfma_f32_16x16x32_bf16 v[46:49], v[146:149], v[220:223], v[46:49]
	v_mfma_f32_16x16x32_bf16 v[30:33], v[146:149], v[228:231], v[30:33]
	v_mfma_f32_16x16x32_bf16 v[26:29], v[180:183], v[228:231], v[26:29]
	v_mfma_f32_16x16x32_bf16 v[10:13], v[180:183], v[244:247], v[10:13]
	v_mfma_f32_16x16x32_bf16 v[14:17], v[146:149], v[244:247], v[14:17]
	v_mfma_f32_16x16x32_bf16 v[62:65], v[176:179], v[216:219], v[62:65]
	v_mfma_f32_16x16x32_bf16 v[58:61], v[184:187], v[216:219], v[58:61]
	v_mfma_f32_16x16x32_bf16 v[42:45], v[184:187], v[224:227], v[42:45]
	v_mfma_f32_16x16x32_bf16 v[46:49], v[176:179], v[224:227], v[46:49]
	v_mfma_f32_16x16x32_bf16 v[30:33], v[176:179], v[240:243], v[30:33]
	v_mfma_f32_16x16x32_bf16 v[26:29], v[184:187], v[240:243], v[26:29]
	v_mfma_f32_16x16x32_bf16 v[10:13], v[184:187], v[248:251], v[10:13]
	v_mfma_f32_16x16x32_bf16 v[14:17], v[176:179], v[248:251], v[14:17]
	s_setprio 0
	s_setprio 1
	v_mfma_f32_16x16x32_bf16 v[54:57], v[188:191], v[212:215], v[54:57]
	v_mfma_f32_16x16x32_bf16 v[50:53], v[204:207], v[212:215], v[50:53]
	v_mfma_f32_16x16x32_bf16 v[34:37], v[204:207], v[220:223], v[34:37]
	v_mfma_f32_16x16x32_bf16 v[38:41], v[188:191], v[220:223], v[38:41]
	v_mfma_f32_16x16x32_bf16 v[22:25], v[188:191], v[228:231], v[22:25]
	v_mfma_f32_16x16x32_bf16 v[18:21], v[204:207], v[228:231], v[18:21]
	v_mfma_f32_16x16x32_bf16 v[2:5], v[204:207], v[244:247], v[2:5]
	v_mfma_f32_16x16x32_bf16 v[6:9], v[188:191], v[244:247], v[6:9]
	v_mfma_f32_16x16x32_bf16 v[54:57], v[200:203], v[216:219], v[54:57]
	v_mfma_f32_16x16x32_bf16 v[50:53], v[208:211], v[216:219], v[50:53]
	v_mfma_f32_16x16x32_bf16 v[34:37], v[208:211], v[224:227], v[34:37]
	v_mfma_f32_16x16x32_bf16 v[38:41], v[200:203], v[224:227], v[38:41]
	v_mfma_f32_16x16x32_bf16 v[22:25], v[200:203], v[240:243], v[22:25]
	v_mfma_f32_16x16x32_bf16 v[18:21], v[208:211], v[240:243], v[18:21]
	v_mfma_f32_16x16x32_bf16 v[2:5], v[208:211], v[248:251], v[2:5]
	v_mfma_f32_16x16x32_bf16 v[6:9], v[200:203], v[248:251], v[6:9]
	s_barrier
	s_setprio 0
	s_add_i32 s61, s61, 2
	s_add_u32 s64, s64, 0x100
	s_addc_u32 s65, s65, 0
	s_add_u32 s53, s53, 0x100
	s_addc_u32 s55, s55, 0
	s_cmp_gt_u32 s61, 61
	s_cbranch_scc0 .LBB0_1203
	s_and_b64 vcc, exec, s[46:47]
	s_cbranch_vccz .LBB0_1206
	s_barrier

; #define PG8_STAGE(bufoff, gbase, voff) do { _Pragma("unroll") for (int _i = 0; _i < 2; ++_i) \
;         __builtin_amdgcn_global_load_lds((const unsigned*)((const char*)(gbase) + (voff)[_i]), (PG8_LAS unsigned*)(lds + (bufoff) + ldsw + _i * 8192), 16, 0, 0); } while (0)
; #define PG8_LDA(dst, b, h) do { _Pragma("unroll") for (int m = 0; m < 4; ++m) _Pragma("unroll") for (int k = 0; k < 2; ++k) dst[m][k] = *(const PG8_LAS bf16x8*)(lds + PG8_SA(b, h) + aoff + m * 2048 + k * 1024); } while (0)
; #define PG8_LDB(dst, b, h) do { _Pragma("unroll") for (int n = 0; n < 2; ++n) _Pragma("unroll") for (int k = 0; k < 2; ++k) dst[n][k] = *(const PG8_LAS bf16x8*)(lds + PG8_SB(b, h) + boff + n * 2048 + k * 1024); } while (0)
; #define PG8_MMA(ai, bj, At, Bt) do { __builtin_amdgcn_s_setprio(1); _Pragma("unroll") for (int m = 0; m < 4; ++m) _Pragma("unroll") for (int n = 0; n < 2; ++n) _Pragma("unroll") for (int k = 0; k < 2; ++k) \
;         acc[ai][bj][m][n] = __builtin_amdgcn_mfma_f32_16x16x32_bf16(Bt[n][k], At[m][k], acc[ai][bj][m][n], 0, 0, 0); __builtin_amdgcn_s_setprio(0); } while (0)
; #define PG8_WAIT_V(n) asm volatile("s_waitcnt vmcnt(" #n ")" ::: "memory")
; #define PG8_WAIT_L(n) asm volatile("s_waitcnt lgkmcnt(" #n ")" ::: "memory")
; template <class Epi, class Sched, bool ALIGN_EPI = false, bool SP2 = false>
; __device__ __forceinline__ void gemm_phase(PG8_LAS unsigned char* lds, const Gemm g, const Sched& S, const Epi& E) {
;     ...
;             const bool last = (t == nt - 2);
;             const char* a1 = cA + (size_t)(t + 1) * kstep;
;             const char* a2 = last ? nA : cA + (size_t)(t + 2) * kstep; const char* b2 = last ? nB : cB + (size_t)(t + 2) * kstep;
;             const char* a3 = a2 + kstep; const char* b3 = b2 + kstep;
;             if (last && has_next) S.a_ready(nxt);
;             if constexpr (SP2) {
;             PG8_LDB(B0, 0, 0); PG8_LDB(B1, 0, 1); PG8_SCHED; PG8_LDA(At, 0, 0); PG8_STAGE(PG8_SA(1, 1), a1 + hstep, voffA);
;             PG8_WAIT_V(8); PG8_WAIT_L(0); PG8_BAR; PG8_MMA(0, 0, At, B0); PG8_MMA(0, 1, At, B1); PG8_BAR; PG8_SCHED;
;             PG8_LDA(At, 0, 1); PG8_STAGE(PG8_SB(0, 0), b2, voffB); PG8_STAGE(PG8_SB(0, 1), b2 + hstep, voffB); PG8_STAGE(PG8_SA(0, 0), a2, voffA);
;             PG8_WAIT_V(8); PG8_WAIT_L(0); PG8_BAR; PG8_MMA(1, 0, At, B0); PG8_MMA(1, 1, At, B1); PG8_BAR; PG8_SCHED;
.LBB0_1478:
	v_add_u32_e32 v144, s31, v201
	v_add_u32_e32 v160, s52, v201
	ds_read_b128 v[132:135], v144
	ds_read_b128 v[136:139], v144 offset:1024
	ds_read_b128 v[140:143], v144 offset:2048
	ds_read_b128 v[144:147], v144 offset:3072
	ds_read_b128 v[148:151], v160
	ds_read_b128 v[152:155], v160 offset:1024
	ds_read_b128 v[156:159], v160 offset:2048
	ds_read_b128 v[160:163], v160 offset:3072
	s_add_u32 s50, s82, 0xfff00080
	s_addc_u32 s56, s83, -1
	s_and_b64 s[34:35], s[84:85], exec
	s_cselect_b32 s87, s65, s56
	s_cselect_b32 s86, s69, s50
	s_cselect_b32 s85, s67, s88
	s_cselect_b32 s84, s77, s79
	v_lshl_add_u64 v[192:193], s[82:83], 0, v[220:221]
	s_add_i32 m0, s28, 0xc000
	ds_read_b128 v[164:167], v242
	ds_read_b128 v[168:171], v242 offset:1024
	ds_read_b128 v[172:175], v242 offset:2048
	ds_read_b128 v[176:179], v242 offset:3072
	ds_read_b128 v[180:183], v242 offset:4096
	ds_read_b128 v[184:187], v242 offset:5120
	ds_read_b128 v[188:191], v242 offset:6144
	ds_read_b128 v[226:229], v242 offset:7168
	global_load_lds_dwordx4 v[192:193], off
	v_lshl_add_u64 v[192:193], s[82:83], 0, v[222:223]
	s_add_i32 m0, s28, 0xe000
	s_nop 0
	global_load_lds_dwordx4 v[192:193], off
	s_waitcnt vmcnt(8)
	s_waitcnt lgkmcnt(0)
	s_setprio 1
	s_barrier
	v_mfma_f32_16x16x32_bf16 v[126:129], v[132:135], v[164:167], v[126:129]
	v_mfma_f32_16x16x32_bf16 v[46:49], v[140:143], v[164:167], v[46:49]
	v_mfma_f32_16x16x32_bf16 v[122:125], v[140:143], v[172:175], v[122:125]
	v_mfma_f32_16x16x32_bf16 v[118:121], v[132:135], v[172:175], v[118:121]
	v_mfma_f32_16x16x32_bf16 v[110:113], v[132:135], v[180:183], v[110:113]
	v_mfma_f32_16x16x32_bf16 v[114:117], v[140:143], v[180:183], v[114:117]
	v_mfma_f32_16x16x32_bf16 v[106:109], v[140:143], v[188:191], v[106:109]
	v_mfma_f32_16x16x32_bf16 v[102:105], v[132:135], v[188:191], v[102:105]
	v_mfma_f32_16x16x32_bf16 v[126:129], v[136:139], v[168:171], v[126:129]
	v_mfma_f32_16x16x32_bf16 v[46:49], v[144:147], v[168:171], v[46:49]
	v_mfma_f32_16x16x32_bf16 v[122:125], v[144:147], v[176:179], v[122:125]
	v_mfma_f32_16x16x32_bf16 v[118:121], v[136:139], v[176:179], v[118:121]
	v_mfma_f32_16x16x32_bf16 v[110:113], v[136:139], v[184:187], v[110:113]
	v_mfma_f32_16x16x32_bf16 v[114:117], v[144:147], v[184:187], v[114:117]
	v_mfma_f32_16x16x32_bf16 v[106:109], v[144:147], v[226:229], v[106:109]
	v_mfma_f32_16x16x32_bf16 v[102:105], v[136:139], v[226:229], v[102:105]
	s_setprio 0
	s_setprio 1
	v_mfma_f32_16x16x32_bf16 v[54:57], v[148:151], v[164:167], v[54:57]
	v_mfma_f32_16x16x32_bf16 v[38:41], v[156:159], v[164:167], v[38:41]
	v_mfma_f32_16x16x32_bf16 v[30:33], v[156:159], v[172:175], v[30:33]
	v_mfma_f32_16x16x32_bf16 v[58:61], v[148:151], v[172:175], v[58:61]
	v_mfma_f32_16x16x32_bf16 v[62:65], v[148:151], v[180:183], v[62:65]
	v_mfma_f32_16x16x32_bf16 v[22:25], v[156:159], v[180:183], v[22:25]
	v_mfma_f32_16x16x32_bf16 v[50:53], v[156:159], v[188:191], v[50:53]
	v_mfma_f32_16x16x32_bf16 v[98:101], v[148:151], v[188:191], v[98:101]
	v_mfma_f32_16x16x32_bf16 v[54:57], v[152:155], v[168:171], v[54:57]
	v_mfma_f32_16x16x32_bf16 v[38:41], v[160:163], v[168:171], v[38:41]
	v_mfma_f32_16x16x32_bf16 v[30:33], v[160:163], v[176:179], v[30:33]
	v_mfma_f32_16x16x32_bf16 v[58:61], v[152:155], v[176:179], v[58:61]
	v_mfma_f32_16x16x32_bf16 v[62:65], v[152:155], v[184:187], v[62:65]
	v_mfma_f32_16x16x32_bf16 v[22:25], v[160:163], v[184:187], v[22:25]
	v_mfma_f32_16x16x32_bf16 v[50:53], v[160:163], v[226:229], v[50:53]
	v_mfma_f32_16x16x32_bf16 v[98:101], v[152:155], v[226:229], v[98:101]
	s_barrier
	s_setprio 0
	s_add_i32 s34, s31, s45
	v_lshl_add_u64 v[192:193], s[84:85], 0, v[208:209]
	s_mov_b32 m0, s34
	ds_read_b128 v[164:167], v242 offset:16384
	ds_read_b128 v[168:171], v242 offset:17408
	ds_read_b128 v[172:175], v242 offset:18432
	ds_read_b128 v[176:179], v242 offset:19456
	ds_read_b128 v[180:183], v242 offset:20480
	ds_read_b128 v[184:187], v242 offset:21504
	ds_read_b128 v[188:191], v242 offset:22528
	ds_read_b128 v[226:229], v242 offset:23552
	global_load_lds_dwordx4 v[192:193], off
	s_add_i32 m0, s34, 0x2000
	s_add_u32 s34, s84, 0x100000
	v_lshl_add_u64 v[194:195], s[84:85], 0, v[212:213]
	s_addc_u32 s35, s85, 0
	s_add_i32 s50, s52, s45
	global_load_lds_dwordx4 v[194:195], off
	v_lshl_add_u64 v[230:231], s[34:35], 0, v[208:209]
	s_mov_b32 m0, s50
	v_lshl_add_u64 v[232:233], s[86:87], 0, v[210:211]
	global_load_lds_dwordx4 v[230:231], off
	v_lshl_add_u64 v[230:231], s[34:35], 0, v[212:213]
	s_add_i32 m0, s50, 0x2000
	s_nop 0
	global_load_lds_dwordx4 v[230:231], off
	v_lshl_add_u64 v[230:231], s[86:87], 0, v[206:207]
	s_mov_b32 m0, s28
	s_nop 0
	global_load_lds_dwordx4 v[230:231], off
	s_mov_b32 m0, s29
	s_nop 0
	global_load_lds_dwordx4 v[232:233], off
	s_waitcnt vmcnt(8)
	s_waitcnt lgkmcnt(0)
	s_setprio 1
	s_barrier
; #define PG8_STAGE(bufoff, gbase, voff) do { _Pragma("unroll") for (int _i = 0; _i < 2; ++_i) \
;         __builtin_amdgcn_global_load_lds((const unsigned*)((const char*)(gbase) + (voff)[_i]), (PG8_LAS unsigned*)(lds + (bufoff) + ldsw + _i * 8192), 16, 0, 0); } while (0)
; #define PG8_LDA(dst, b, h) do { _Pragma("unroll") for (int m = 0; m < 4; ++m) _Pragma("unroll") for (int k = 0; k < 2; ++k) dst[m][k] = *(const PG8_LAS bf16x8*)(lds + PG8_SA(b, h) + aoff + m * 2048 + k * 1024); } while (0)
; #define PG8_LDB(dst, b, h) do { _Pragma("unroll") for (int n = 0; n < 2; ++n) _Pragma("unroll") for (int k = 0; k < 2; ++k) dst[n][k] = *(const PG8_LAS bf16x8*)(lds + PG8_SB(b, h) + boff + n * 2048 + k * 1024); } while (0)
; #define PG8_MMA(ai, bj, At, Bt) do { __builtin_amdgcn_s_setprio(1); _Pragma("unroll") for (int m = 0; m < 4; ++m) _Pragma("unroll") for (int n = 0; n < 2; ++n) _Pragma("unroll") for (int k = 0; k < 2; ++k) \
;         acc[ai][bj][m][n] = __builtin_amdgcn_mfma_f32_16x16x32_bf16(Bt[n][k], At[m][k], acc[ai][bj][m][n], 0, 0, 0); __builtin_amdgcn_s_setprio(0); } while (0)
; #define PG8_WAIT_V(n) asm volatile("s_waitcnt vmcnt(" #n ")" ::: "memory")
; #define PG8_WAIT_L(n) asm volatile("s_waitcnt lgkmcnt(" #n ")" ::: "memory")
; #define PG8_BAR __builtin_amdgcn_s_barrier()
; #define PG8_SCHED __builtin_amdgcn_sched_barrier(0)
; template <class Epi, class Sched, bool ALIGN_EPI = false, bool SP2 = false>
; __device__ __forceinline__ void gemm_phase(PG8_LAS unsigned char* lds, const Gemm g, const Sched& S, const Epi& E) {
;     ...
;             PG8_WAIT_V(8); PG8_WAIT_L(0); PG8_BAR; PG8_MMA(1, 0, At, B0); PG8_MMA(1, 1, At, B1); PG8_BAR; PG8_SCHED;
;             PG8_LDB(B0, 1, 0); PG8_LDB(B1, 1, 1); PG8_SCHED; PG8_LDA(At, 1, 0); PG8_STAGE(PG8_SA(0, 1), a2 + hstep, voffA);
;             PG8_WAIT_V(8); PG8_WAIT_L(0); PG8_BAR; PG8_MMA(0, 0, At, B0); PG8_MMA(0, 1, At, B1); PG8_BAR; PG8_SCHED;
	v_mfma_f32_16x16x32_bf16 v[78:81], v[132:135], v[164:167], v[78:81]
	v_mfma_f32_16x16x32_bf16 v[14:17], v[140:143], v[164:167], v[14:17]
	v_mfma_f32_16x16x32_bf16 v[94:97], v[140:143], v[172:175], v[94:97]
	v_mfma_f32_16x16x32_bf16 v[66:69], v[132:135], v[172:175], v[66:69]
	v_mfma_f32_16x16x32_bf16 v[70:73], v[132:135], v[180:183], v[70:73]
	v_mfma_f32_16x16x32_bf16 v[90:93], v[140:143], v[180:183], v[90:93]
	v_mfma_f32_16x16x32_bf16 v[10:13], v[140:143], v[188:191], v[10:13]
	v_mfma_f32_16x16x32_bf16 v[74:77], v[132:135], v[188:191], v[74:77]
	v_mfma_f32_16x16x32_bf16 v[78:81], v[136:139], v[168:171], v[78:81]
	v_mfma_f32_16x16x32_bf16 v[14:17], v[144:147], v[168:171], v[14:17]
	v_mfma_f32_16x16x32_bf16 v[94:97], v[144:147], v[176:179], v[94:97]
	v_mfma_f32_16x16x32_bf16 v[66:69], v[136:139], v[176:179], v[66:69]
	v_mfma_f32_16x16x32_bf16 v[70:73], v[136:139], v[184:187], v[70:73]
	v_mfma_f32_16x16x32_bf16 v[90:93], v[144:147], v[184:187], v[90:93]
	v_mfma_f32_16x16x32_bf16 v[10:13], v[144:147], v[226:229], v[10:13]
	v_mfma_f32_16x16x32_bf16 v[74:77], v[136:139], v[226:229], v[74:77]
	s_setprio 0
	s_setprio 1
	v_mfma_f32_16x16x32_bf16 v[42:45], v[148:151], v[164:167], v[42:45]
	v_mfma_f32_16x16x32_bf16 v[2:5], v[156:159], v[164:167], v[2:5]
	v_mfma_f32_16x16x32_bf16 v[6:9], v[156:159], v[172:175], v[6:9]
	v_mfma_f32_16x16x32_bf16 v[34:37], v[148:151], v[172:175], v[34:37]
	v_mfma_f32_16x16x32_bf16 v[86:89], v[148:151], v[180:183], v[86:89]
	v_mfma_f32_16x16x32_bf16 v[26:29], v[156:159], v[180:183], v[26:29]
	v_mfma_f32_16x16x32_bf16 v[18:21], v[156:159], v[188:191], v[18:21]
	v_mfma_f32_16x16x32_bf16 v[82:85], v[148:151], v[188:191], v[82:85]
	v_mfma_f32_16x16x32_bf16 v[42:45], v[152:155], v[168:171], v[42:45]
	v_mfma_f32_16x16x32_bf16 v[2:5], v[160:163], v[168:171], v[2:5]
	v_mfma_f32_16x16x32_bf16 v[6:9], v[160:163], v[176:179], v[6:9]
	v_mfma_f32_16x16x32_bf16 v[34:37], v[152:155], v[176:179], v[34:37]
	v_mfma_f32_16x16x32_bf16 v[86:89], v[152:155], v[184:187], v[86:89]
	v_mfma_f32_16x16x32_bf16 v[26:29], v[160:163], v[184:187], v[26:29]
	v_mfma_f32_16x16x32_bf16 v[18:21], v[160:163], v[226:229], v[18:21]
	v_mfma_f32_16x16x32_bf16 v[82:85], v[152:155], v[226:229], v[82:85]
	s_barrier
	s_setprio 0
	s_add_i32 s50, 0, 0x18000
	s_add_i32 s56, 0, 0x1c000
	v_add_u32_e32 v144, s50, v201
	v_add_u32_e32 v160, s56, v201
	ds_read_b128 v[132:135], v144
	ds_read_b128 v[136:139], v144 offset:1024
	ds_read_b128 v[140:143], v144 offset:2048
	ds_read_b128 v[144:147], v144 offset:3072
	ds_read_b128 v[148:151], v160
	ds_read_b128 v[152:155], v160 offset:1024
	ds_read_b128 v[156:159], v160 offset:2048
	ds_read_b128 v[160:163], v160 offset:3072
	s_add_u32 s34, s86, 0x100000
	s_addc_u32 s35, s87, 0
	s_mov_b32 m0, s16
	v_lshl_add_u64 v[246:247], s[34:35], 0, v[206:207]
	ds_read_b128 v[164:167], v242 offset:32768
	ds_read_b128 v[168:171], v242 offset:33792
	ds_read_b128 v[172:175], v242 offset:34816
	ds_read_b128 v[176:179], v242 offset:35840
	ds_read_b128 v[180:183], v242 offset:36864
	ds_read_b128 v[184:187], v242 offset:37888
	ds_read_b128 v[188:191], v242 offset:38912
	ds_read_b128 v[226:229], v242 offset:39936
	global_load_lds_dwordx4 v[246:247], off
	v_lshl_add_u64 v[246:247], s[34:35], 0, v[210:211]
	s_mov_b32 m0, s17
	s_nop 0
	global_load_lds_dwordx4 v[246:247], off
	s_waitcnt vmcnt(8)
	s_waitcnt lgkmcnt(0)
	s_setprio 1
	s_barrier
	v_mfma_f32_16x16x32_bf16 v[126:129], v[132:135], v[164:167], v[126:129]
	v_mfma_f32_16x16x32_bf16 v[46:49], v[140:143], v[164:167], v[46:49]
	v_mfma_f32_16x16x32_bf16 v[122:125], v[140:143], v[172:175], v[122:125]
	v_mfma_f32_16x16x32_bf16 v[118:121], v[132:135], v[172:175], v[118:121]
	v_mfma_f32_16x16x32_bf16 v[110:113], v[132:135], v[180:183], v[110:113]
	v_mfma_f32_16x16x32_bf16 v[114:117], v[140:143], v[180:183], v[114:117]
	v_mfma_f32_16x16x32_bf16 v[106:109], v[140:143], v[188:191], v[106:109]
	v_mfma_f32_16x16x32_bf16 v[102:105], v[132:135], v[188:191], v[102:105]
	v_mfma_f32_16x16x32_bf16 v[126:129], v[136:139], v[168:171], v[126:129]
	v_mfma_f32_16x16x32_bf16 v[46:49], v[144:147], v[168:171], v[46:49]
	v_mfma_f32_16x16x32_bf16 v[122:125], v[144:147], v[176:179], v[122:125]
	v_mfma_f32_16x16x32_bf16 v[118:121], v[136:139], v[176:179], v[118:121]
	v_mfma_f32_16x16x32_bf16 v[110:113], v[136:139], v[184:187], v[110:113]
	v_mfma_f32_16x16x32_bf16 v[114:117], v[144:147], v[184:187], v[114:117]
	v_mfma_f32_16x16x32_bf16 v[106:109], v[144:147], v[226:229], v[106:109]
	v_mfma_f32_16x16x32_bf16 v[102:105], v[136:139], v[226:229], v[102:105]
	s_setprio 0
	s_setprio 1
	v_mfma_f32_16x16x32_bf16 v[54:57], v[148:151], v[164:167], v[54:57]
	v_mfma_f32_16x16x32_bf16 v[38:41], v[156:159], v[164:167], v[38:41]
	v_mfma_f32_16x16x32_bf16 v[30:33], v[156:159], v[172:175], v[30:33]
	v_mfma_f32_16x16x32_bf16 v[58:61], v[148:151], v[172:175], v[58:61]
	v_mfma_f32_16x16x32_bf16 v[62:65], v[148:151], v[180:183], v[62:65]
	v_mfma_f32_16x16x32_bf16 v[22:25], v[156:159], v[180:183], v[22:25]
	v_mfma_f32_16x16x32_bf16 v[50:53], v[156:159], v[188:191], v[50:53]
	v_mfma_f32_16x16x32_bf16 v[98:101], v[148:151], v[188:191], v[98:101]
	v_mfma_f32_16x16x32_bf16 v[54:57], v[152:155], v[168:171], v[54:57]
	v_mfma_f32_16x16x32_bf16 v[38:41], v[160:163], v[168:171], v[38:41]
	v_mfma_f32_16x16x32_bf16 v[30:33], v[160:163], v[176:179], v[30:33]
	v_mfma_f32_16x16x32_bf16 v[58:61], v[152:155], v[176:179], v[58:61]
	v_mfma_f32_16x16x32_bf16 v[62:65], v[152:155], v[184:187], v[62:65]
	v_mfma_f32_16x16x32_bf16 v[22:25], v[160:163], v[184:187], v[22:25]
	v_mfma_f32_16x16x32_bf16 v[50:53], v[160:163], v[226:229], v[50:53]
	v_mfma_f32_16x16x32_bf16 v[98:101], v[152:155], v[226:229], v[98:101]
	s_barrier
; #define PG8_STAGE(bufoff, gbase, voff) do { _Pragma("unroll") for (int _i = 0; _i < 2; ++_i) \
;         __builtin_amdgcn_global_load_lds((const unsigned*)((const char*)(gbase) + (voff)[_i]), (PG8_LAS unsigned*)(lds + (bufoff) + ldsw + _i * 8192), 16, 0, 0); } while (0)
; #define PG8_LDA(dst, b, h) do { _Pragma("unroll") for (int m = 0; m < 4; ++m) _Pragma("unroll") for (int k = 0; k < 2; ++k) dst[m][k] = *(const PG8_LAS bf16x8*)(lds + PG8_SA(b, h) + aoff + m * 2048 + k * 1024); } while (0)
; #define PG8_MMA(ai, bj, At, Bt) do { __builtin_amdgcn_s_setprio(1); _Pragma("unroll") for (int m = 0; m < 4; ++m) _Pragma("unroll") for (int n = 0; n < 2; ++n) _Pragma("unroll") for (int k = 0; k < 2; ++k) \
;         acc[ai][bj][m][n] = __builtin_amdgcn_mfma_f32_16x16x32_bf16(Bt[n][k], At[m][k], acc[ai][bj][m][n], 0, 0, 0); __builtin_amdgcn_s_setprio(0); } while (0)
; #define PG8_WAIT_V(n) asm volatile("s_waitcnt vmcnt(" #n ")" ::: "memory")
; #define PG8_WAIT_L(n) asm volatile("s_waitcnt lgkmcnt(" #n ")" ::: "memory")
; #define PG8_BAR __builtin_amdgcn_s_barrier()
; #define PG8_SCHED __builtin_amdgcn_sched_barrier(0)
; template <class Epi, class Sched, bool ALIGN_EPI = false, bool SP2 = false>
; __device__ __forceinline__ void gemm_phase(PG8_LAS unsigned char* lds, const Gemm g, const Sched& S, const Epi& E) {
;     ...
;         for (int t = 0; t < nt; t += 2) {
;             const bool last = (t == nt - 2);
;             const char* a1 = cA + (size_t)(t + 1) * kstep;
;             const char* a2 = last ? nA : cA + (size_t)(t + 2) * kstep; const char* b2 = last ? nB : cB + (size_t)(t + 2) * kstep;
;     ...
;             PG8_LDA(At, 1, 1); PG8_STAGE(PG8_SB(1, 0), b3, voffB); PG8_STAGE(PG8_SB(1, 1), b3 + hstep, voffB); PG8_STAGE(PG8_SA(1, 0), a3, voffA);
;             PG8_WAIT_V(8); PG8_WAIT_L(0); PG8_BAR; PG8_MMA(1, 0, At, B0); PG8_MMA(1, 1, At, B1); PG8_BAR; PG8_SCHED;
	s_setprio 0
	s_add_i32 s34, s50, s45
	v_lshl_add_u64 v[192:193], v[192:193], 0, s[54:55]
	s_mov_b32 m0, s34
	ds_read_b128 v[164:167], v242 offset:49152
	ds_read_b128 v[168:171], v242 offset:50176
	ds_read_b128 v[172:175], v242 offset:51200
	ds_read_b128 v[176:179], v242 offset:52224
	ds_read_b128 v[180:183], v242 offset:53248
	ds_read_b128 v[184:187], v242 offset:54272
	ds_read_b128 v[188:191], v242 offset:55296
	ds_read_b128 v[226:229], v242 offset:56320
	global_load_lds_dwordx4 v[192:193], off
	s_add_i32 m0, s34, 0x2000
	s_add_u32 s34, s84, 0x100080
	v_lshl_add_u64 v[192:193], v[194:195], 0, s[54:55]
	s_addc_u32 s35, s85, 0
	s_add_i32 s50, s56, s45
	global_load_lds_dwordx4 v[192:193], off
	v_lshl_add_u64 v[192:193], s[34:35], 0, v[208:209]
	s_mov_b32 m0, s50
	s_nop 0
	global_load_lds_dwordx4 v[192:193], off
	v_lshl_add_u64 v[192:193], s[34:35], 0, v[212:213]
	s_add_i32 m0, s50, 0x2000
	s_nop 0
	global_load_lds_dwordx4 v[192:193], off
	v_lshl_add_u64 v[192:193], v[230:231], 0, s[54:55]
	s_mov_b32 m0, s39
	s_nop 0
	global_load_lds_dwordx4 v[192:193], off
	v_lshl_add_u64 v[192:193], v[232:233], 0, s[54:55]
	s_mov_b32 m0, s46
	s_nop 0
	global_load_lds_dwordx4 v[192:193], off
	s_waitcnt vmcnt(8)
	s_waitcnt lgkmcnt(0)
	s_setprio 1
	s_barrier
	v_mfma_f32_16x16x32_bf16 v[78:81], v[132:135], v[164:167], v[78:81]
	v_mfma_f32_16x16x32_bf16 v[14:17], v[140:143], v[164:167], v[14:17]
	v_mfma_f32_16x16x32_bf16 v[94:97], v[140:143], v[172:175], v[94:97]
	v_mfma_f32_16x16x32_bf16 v[66:69], v[132:135], v[172:175], v[66:69]
	v_mfma_f32_16x16x32_bf16 v[70:73], v[132:135], v[180:183], v[70:73]
	v_mfma_f32_16x16x32_bf16 v[90:93], v[140:143], v[180:183], v[90:93]
	v_mfma_f32_16x16x32_bf16 v[10:13], v[140:143], v[188:191], v[10:13]
	v_mfma_f32_16x16x32_bf16 v[74:77], v[132:135], v[188:191], v[74:77]
	v_mfma_f32_16x16x32_bf16 v[78:81], v[136:139], v[168:171], v[78:81]
	v_mfma_f32_16x16x32_bf16 v[14:17], v[144:147], v[168:171], v[14:17]
	v_mfma_f32_16x16x32_bf16 v[94:97], v[144:147], v[176:179], v[94:97]
	v_mfma_f32_16x16x32_bf16 v[66:69], v[136:139], v[176:179], v[66:69]
	v_mfma_f32_16x16x32_bf16 v[70:73], v[136:139], v[184:187], v[70:73]
	v_mfma_f32_16x16x32_bf16 v[90:93], v[144:147], v[184:187], v[90:93]
	v_mfma_f32_16x16x32_bf16 v[10:13], v[144:147], v[226:229], v[10:13]
	v_mfma_f32_16x16x32_bf16 v[74:77], v[136:139], v[226:229], v[74:77]
	s_setprio 0
	s_setprio 1
	v_mfma_f32_16x16x32_bf16 v[42:45], v[148:151], v[164:167], v[42:45]
	v_mfma_f32_16x16x32_bf16 v[2:5], v[156:159], v[164:167], v[2:5]
	v_mfma_f32_16x16x32_bf16 v[6:9], v[156:159], v[172:175], v[6:9]
	v_mfma_f32_16x16x32_bf16 v[34:37], v[148:151], v[172:175], v[34:37]
	v_mfma_f32_16x16x32_bf16 v[86:89], v[148:151], v[180:183], v[86:89]
	v_mfma_f32_16x16x32_bf16 v[26:29], v[156:159], v[180:183], v[26:29]
	v_mfma_f32_16x16x32_bf16 v[18:21], v[156:159], v[188:191], v[18:21]
	v_mfma_f32_16x16x32_bf16 v[82:85], v[148:151], v[188:191], v[82:85]
	v_mfma_f32_16x16x32_bf16 v[42:45], v[152:155], v[168:171], v[42:45]
	v_mfma_f32_16x16x32_bf16 v[2:5], v[160:163], v[168:171], v[2:5]
	v_mfma_f32_16x16x32_bf16 v[6:9], v[160:163], v[176:179], v[6:9]
	v_mfma_f32_16x16x32_bf16 v[34:37], v[152:155], v[176:179], v[34:37]
	v_mfma_f32_16x16x32_bf16 v[86:89], v[152:155], v[184:187], v[86:89]
	v_mfma_f32_16x16x32_bf16 v[26:29], v[160:163], v[184:187], v[26:29]
	v_mfma_f32_16x16x32_bf16 v[18:21], v[160:163], v[226:229], v[18:21]
	v_mfma_f32_16x16x32_bf16 v[82:85], v[152:155], v[226:229], v[82:85]
	s_barrier
	s_setprio 0
	s_add_i32 s89, s89, 2
	s_add_u32 s82, s82, 0x100
	s_addc_u32 s83, s83, 0
	s_add_u32 s79, s79, 0x100
	s_addc_u32 s88, s88, 0
	s_cmp_gt_u32 s89, 61
	s_cbranch_scc1 .LBB0_1490

; #define PG8_STAGE(bufoff, gbase, voff) do { _Pragma("unroll") for (int _i = 0; _i < 2; ++_i) \
;         __builtin_amdgcn_global_load_lds((const unsigned*)((const char*)(gbase) + (voff)[_i]), (PG8_LAS unsigned*)(lds + (bufoff) + ldsw + _i * 8192), 16, 0, 0); } while (0)
; #define PG8_LDA(dst, b, h) do { _Pragma("unroll") for (int m = 0; m < 4; ++m) _Pragma("unroll") for (int k = 0; k < 2; ++k) dst[m][k] = *(const PG8_LAS bf16x8*)(lds + PG8_SA(b, h) + aoff + m * 2048 + k * 1024); } while (0)
; #define PG8_LDB(dst, b, h) do { _Pragma("unroll") for (int n = 0; n < 2; ++n) _Pragma("unroll") for (int k = 0; k < 2; ++k) dst[n][k] = *(const PG8_LAS bf16x8*)(lds + PG8_SB(b, h) + boff + n * 2048 + k * 1024); } while (0)
; #define PG8_MMA(ai, bj, At, Bt) do { __builtin_amdgcn_s_setprio(1); _Pragma("unroll") for (int m = 0; m < 4; ++m) _Pragma("unroll") for (int n = 0; n < 2; ++n) _Pragma("unroll") for (int k = 0; k < 2; ++k) \
;         acc[ai][bj][m][n] = __builtin_amdgcn_mfma_f32_16x16x32_bf16(Bt[n][k], At[m][k], acc[ai][bj][m][n], 0, 0, 0); __builtin_amdgcn_s_setprio(0); } while (0)
; #define PG8_WAIT_V(n) asm volatile("s_waitcnt vmcnt(" #n ")" ::: "memory")
; #define PG8_WAIT_L(n) asm volatile("s_waitcnt lgkmcnt(" #n ")" ::: "memory")
; template <class Epi, class Sched, bool ALIGN_EPI = false, bool SP2 = false>
; __device__ __forceinline__ void gemm_phase(PG8_LAS unsigned char* lds, const Gemm g, const Sched& S, const Epi& E) {
;     ...
;             const bool last = (t == nt - 2);
;             const char* a1 = cA + (size_t)(t + 1) * kstep;
;             const char* a2 = last ? nA : cA + (size_t)(t + 2) * kstep; const char* b2 = last ? nB : cB + (size_t)(t + 2) * kstep;
;             const char* a3 = a2 + kstep; const char* b3 = b2 + kstep;
;             if (last && has_next) S.a_ready(nxt);
;             if constexpr (SP2) {
;             PG8_LDB(B0, 0, 0); PG8_LDB(B1, 0, 1); PG8_SCHED; PG8_LDA(At, 0, 0); PG8_STAGE(PG8_SA(1, 1), a1 + hstep, voffA);
;             PG8_WAIT_V(8); PG8_WAIT_L(0); PG8_BAR; PG8_MMA(0, 0, At, B0); PG8_MMA(0, 1, At, B1); PG8_BAR; PG8_SCHED;
;             PG8_LDA(At, 0, 1); PG8_STAGE(PG8_SB(0, 0), b2, voffB); PG8_STAGE(PG8_SB(0, 1), b2 + hstep, voffB); PG8_STAGE(PG8_SA(0, 0), a2, voffA);
;             PG8_WAIT_V(8); PG8_WAIT_L(0); PG8_BAR; PG8_MMA(1, 0, At, B0); PG8_MMA(1, 1, At, B1); PG8_BAR; PG8_SCHED;
.LBB0_1731:
	ds_read_b128 v[170:173], v166
	ds_read_b128 v[174:177], v166 offset:1024
	ds_read_b128 v[178:181], v166 offset:2048
	ds_read_b128 v[182:185], v166 offset:3072
	ds_read_b128 v[186:189], v167
	ds_read_b128 v[190:193], v167 offset:1024
	ds_read_b128 v[196:199], v167 offset:2048
	ds_read_b128 v[202:205], v167 offset:3072
	s_add_u32 s48, s40, 0x100
	s_addc_u32 s49, s41, 0
	s_cmpk_eq_i32 s56, 0xa8
	s_cselect_b32 s53, s7, s49
	s_cselect_b32 s52, s6, s48
	s_cselect_b32 s51, s39, s55
	s_cselect_b32 s50, s38, s54
	v_lshl_add_u64 v[146:147], s[40:41], 0, v[138:139]
	s_add_i32 m0, s16, 0xc000
	ds_read_b128 v[206:209], v168
	ds_read_b128 v[210:213], v168 offset:1024
	ds_read_b128 v[214:217], v168 offset:2048
	ds_read_b128 v[218:221], v168 offset:3072
	ds_read_b128 v[222:225], v168 offset:4096
	ds_read_b128 v[226:229], v168 offset:5120
	ds_read_b128 v[230:233], v168 offset:6144
	ds_read_b128 v[234:237], v168 offset:7168
	global_load_lds_dwordx4 v[146:147], off
	v_lshl_add_u64 v[146:147], s[40:41], 0, v[140:141]
	s_add_i32 m0, s16, 0xe000
	s_nop 0
	global_load_lds_dwordx4 v[146:147], off
	s_waitcnt vmcnt(8)
	s_waitcnt lgkmcnt(0)
	s_setprio 1
	s_barrier
	v_mfma_f32_16x16x32_bf16 v[126:129], v[170:173], v[206:209], v[126:129]
	v_mfma_f32_16x16x32_bf16 v[122:125], v[178:181], v[206:209], v[122:125]
	v_mfma_f32_16x16x32_bf16 v[106:109], v[178:181], v[214:217], v[106:109]
	v_mfma_f32_16x16x32_bf16 v[110:113], v[170:173], v[214:217], v[110:113]
	v_mfma_f32_16x16x32_bf16 v[94:97], v[170:173], v[222:225], v[94:97]
	v_mfma_f32_16x16x32_bf16 v[90:93], v[178:181], v[222:225], v[90:93]
	v_mfma_f32_16x16x32_bf16 v[74:77], v[178:181], v[230:233], v[74:77]
	v_mfma_f32_16x16x32_bf16 v[78:81], v[170:173], v[230:233], v[78:81]
	v_mfma_f32_16x16x32_bf16 v[126:129], v[174:177], v[210:213], v[126:129]
	v_mfma_f32_16x16x32_bf16 v[122:125], v[182:185], v[210:213], v[122:125]
	v_mfma_f32_16x16x32_bf16 v[106:109], v[182:185], v[218:221], v[106:109]
	v_mfma_f32_16x16x32_bf16 v[110:113], v[174:177], v[218:221], v[110:113]
	v_mfma_f32_16x16x32_bf16 v[94:97], v[174:177], v[226:229], v[94:97]
	v_mfma_f32_16x16x32_bf16 v[90:93], v[182:185], v[226:229], v[90:93]
	v_mfma_f32_16x16x32_bf16 v[74:77], v[182:185], v[234:237], v[74:77]
	v_mfma_f32_16x16x32_bf16 v[78:81], v[174:177], v[234:237], v[78:81]
	s_setprio 0
	s_setprio 1
	v_mfma_f32_16x16x32_bf16 v[118:121], v[186:189], v[206:209], v[118:121]
	v_mfma_f32_16x16x32_bf16 v[114:117], v[196:199], v[206:209], v[114:117]
	v_mfma_f32_16x16x32_bf16 v[98:101], v[196:199], v[214:217], v[98:101]
	v_mfma_f32_16x16x32_bf16 v[102:105], v[186:189], v[214:217], v[102:105]
	v_mfma_f32_16x16x32_bf16 v[86:89], v[186:189], v[222:225], v[86:89]
	v_mfma_f32_16x16x32_bf16 v[82:85], v[196:199], v[222:225], v[82:85]
	v_mfma_f32_16x16x32_bf16 v[66:69], v[196:199], v[230:233], v[66:69]
	v_mfma_f32_16x16x32_bf16 v[70:73], v[186:189], v[230:233], v[70:73]
	v_mfma_f32_16x16x32_bf16 v[118:121], v[190:193], v[210:213], v[118:121]
	v_mfma_f32_16x16x32_bf16 v[114:117], v[202:205], v[210:213], v[114:117]
	v_mfma_f32_16x16x32_bf16 v[98:101], v[202:205], v[218:221], v[98:101]
	v_mfma_f32_16x16x32_bf16 v[102:105], v[190:193], v[218:221], v[102:105]
	v_mfma_f32_16x16x32_bf16 v[86:89], v[190:193], v[226:229], v[86:89]
	v_mfma_f32_16x16x32_bf16 v[82:85], v[202:205], v[226:229], v[82:85]
	v_mfma_f32_16x16x32_bf16 v[66:69], v[202:205], v[234:237], v[66:69]
	v_mfma_f32_16x16x32_bf16 v[70:73], v[190:193], v[234:237], v[70:73]
	s_barrier
	s_setprio 0
	s_add_i32 s40, s31, s3
	v_lshl_add_u64 v[146:147], s[50:51], 0, v[132:133]
	s_mov_b32 m0, s40
	ds_read_b128 v[206:209], v168 offset:16384
	ds_read_b128 v[210:213], v168 offset:17408
	ds_read_b128 v[214:217], v168 offset:18432
	ds_read_b128 v[218:221], v168 offset:19456
	ds_read_b128 v[222:225], v168 offset:20480
	ds_read_b128 v[226:229], v168 offset:21504
	ds_read_b128 v[230:233], v168 offset:22528
	ds_read_b128 v[234:237], v168 offset:23552
	global_load_lds_dwordx4 v[146:147], off
	s_add_i32 m0, s40, 0x2000
	s_add_u32 s40, s50, 0x2b0000
	v_lshl_add_u64 v[194:195], s[50:51], 0, v[136:137]
	s_addc_u32 s41, s51, 0
	s_add_i32 s57, s35, s3
	global_load_lds_dwordx4 v[194:195], off
	v_lshl_add_u64 v[238:239], s[40:41], 0, v[132:133]
	s_mov_b32 m0, s57
	v_lshl_add_u64 v[240:241], s[52:53], 0, v[134:135]
	global_load_lds_dwordx4 v[238:239], off
	v_lshl_add_u64 v[238:239], s[40:41], 0, v[136:137]
	s_add_i32 m0, s57, 0x2000
	s_nop 0
	global_load_lds_dwordx4 v[238:239], off
	v_lshl_add_u64 v[238:239], s[52:53], 0, v[130:131]
	s_mov_b32 m0, s16
	s_nop 0
	global_load_lds_dwordx4 v[238:239], off
	s_mov_b32 m0, s17
	s_nop 0
	global_load_lds_dwordx4 v[240:241], off
	s_waitcnt vmcnt(8)
	s_waitcnt lgkmcnt(0)
	s_setprio 1
	s_barrier
; #define PG8_STAGE(bufoff, gbase, voff) do { _Pragma("unroll") for (int _i = 0; _i < 2; ++_i) \
;         __builtin_amdgcn_global_load_lds((const unsigned*)((const char*)(gbase) + (voff)[_i]), (PG8_LAS unsigned*)(lds + (bufoff) + ldsw + _i * 8192), 16, 0, 0); } while (0)
; #define PG8_LDA(dst, b, h) do { _Pragma("unroll") for (int m = 0; m < 4; ++m) _Pragma("unroll") for (int k = 0; k < 2; ++k) dst[m][k] = *(const PG8_LAS bf16x8*)(lds + PG8_SA(b, h) + aoff + m * 2048 + k * 1024); } while (0)
; #define PG8_LDB(dst, b, h) do { _Pragma("unroll") for (int n = 0; n < 2; ++n) _Pragma("unroll") for (int k = 0; k < 2; ++k) dst[n][k] = *(const PG8_LAS bf16x8*)(lds + PG8_SB(b, h) + boff + n * 2048 + k * 1024); } while (0)
; #define PG8_MMA(ai, bj, At, Bt) do { __builtin_amdgcn_s_setprio(1); _Pragma("unroll") for (int m = 0; m < 4; ++m) _Pragma("unroll") for (int n = 0; n < 2; ++n) _Pragma("unroll") for (int k = 0; k < 2; ++k) \
;         acc[ai][bj][m][n] = __builtin_amdgcn_mfma_f32_16x16x32_bf16(Bt[n][k], At[m][k], acc[ai][bj][m][n], 0, 0, 0); __builtin_amdgcn_s_setprio(0); } while (0)
; #define PG8_WAIT_V(n) asm volatile("s_waitcnt vmcnt(" #n ")" ::: "memory")
; #define PG8_WAIT_L(n) asm volatile("s_waitcnt lgkmcnt(" #n ")" ::: "memory")
; #define PG8_BAR __builtin_amdgcn_s_barrier()
; #define PG8_SCHED __builtin_amdgcn_sched_barrier(0)
; template <class Epi, class Sched, bool ALIGN_EPI = false, bool SP2 = false>
; __device__ __forceinline__ void gemm_phase(PG8_LAS unsigned char* lds, const Gemm g, const Sched& S, const Epi& E) {
;     ...
;             PG8_WAIT_V(8); PG8_WAIT_L(0); PG8_BAR; PG8_MMA(1, 0, At, B0); PG8_MMA(1, 1, At, B1); PG8_BAR; PG8_SCHED;
;             PG8_LDB(B0, 1, 0); PG8_LDB(B1, 1, 1); PG8_SCHED; PG8_LDA(At, 1, 0); PG8_STAGE(PG8_SA(0, 1), a2 + hstep, voffA);
;             PG8_WAIT_V(8); PG8_WAIT_L(0); PG8_BAR; PG8_MMA(0, 0, At, B0); PG8_MMA(0, 1, At, B1); PG8_BAR; PG8_SCHED;
	v_mfma_f32_16x16x32_bf16 v[62:65], v[170:173], v[206:209], v[62:65]
	v_mfma_f32_16x16x32_bf16 v[58:61], v[178:181], v[206:209], v[58:61]
	v_mfma_f32_16x16x32_bf16 v[42:45], v[178:181], v[214:217], v[42:45]
	v_mfma_f32_16x16x32_bf16 v[46:49], v[170:173], v[214:217], v[46:49]
	v_mfma_f32_16x16x32_bf16 v[30:33], v[170:173], v[222:225], v[30:33]
	v_mfma_f32_16x16x32_bf16 v[26:29], v[178:181], v[222:225], v[26:29]
	v_mfma_f32_16x16x32_bf16 v[10:13], v[178:181], v[230:233], v[10:13]
	v_mfma_f32_16x16x32_bf16 v[14:17], v[170:173], v[230:233], v[14:17]
	v_mfma_f32_16x16x32_bf16 v[62:65], v[174:177], v[210:213], v[62:65]
	v_mfma_f32_16x16x32_bf16 v[58:61], v[182:185], v[210:213], v[58:61]
	v_mfma_f32_16x16x32_bf16 v[42:45], v[182:185], v[218:221], v[42:45]
	v_mfma_f32_16x16x32_bf16 v[46:49], v[174:177], v[218:221], v[46:49]
	v_mfma_f32_16x16x32_bf16 v[30:33], v[174:177], v[226:229], v[30:33]
	v_mfma_f32_16x16x32_bf16 v[26:29], v[182:185], v[226:229], v[26:29]
	v_mfma_f32_16x16x32_bf16 v[10:13], v[182:185], v[234:237], v[10:13]
	v_mfma_f32_16x16x32_bf16 v[14:17], v[174:177], v[234:237], v[14:17]
	s_setprio 0
	s_setprio 1
	v_mfma_f32_16x16x32_bf16 v[54:57], v[186:189], v[206:209], v[54:57]
	v_mfma_f32_16x16x32_bf16 v[50:53], v[196:199], v[206:209], v[50:53]
	v_mfma_f32_16x16x32_bf16 v[34:37], v[196:199], v[214:217], v[34:37]
	v_mfma_f32_16x16x32_bf16 v[38:41], v[186:189], v[214:217], v[38:41]
	v_mfma_f32_16x16x32_bf16 v[22:25], v[186:189], v[222:225], v[22:25]
	v_mfma_f32_16x16x32_bf16 v[18:21], v[196:199], v[222:225], v[18:21]
	v_mfma_f32_16x16x32_bf16 v[2:5], v[196:199], v[230:233], v[2:5]
	v_mfma_f32_16x16x32_bf16 v[6:9], v[186:189], v[230:233], v[6:9]
	v_mfma_f32_16x16x32_bf16 v[54:57], v[190:193], v[210:213], v[54:57]
	v_mfma_f32_16x16x32_bf16 v[50:53], v[202:205], v[210:213], v[50:53]
	v_mfma_f32_16x16x32_bf16 v[34:37], v[202:205], v[218:221], v[34:37]
	v_mfma_f32_16x16x32_bf16 v[38:41], v[190:193], v[218:221], v[38:41]
	v_mfma_f32_16x16x32_bf16 v[22:25], v[190:193], v[226:229], v[22:25]
	v_mfma_f32_16x16x32_bf16 v[18:21], v[202:205], v[226:229], v[18:21]
	v_mfma_f32_16x16x32_bf16 v[2:5], v[202:205], v[234:237], v[2:5]
	v_mfma_f32_16x16x32_bf16 v[6:9], v[190:193], v[234:237], v[6:9]
	s_barrier
	s_setprio 0
	s_add_i32 s57, 0, 0x18000
	v_add_u32_e32 v169, s57, v148
	s_add_i32 s58, 0, 0x1c000
	ds_read_b128 v[170:173], v169
	ds_read_b128 v[174:177], v169 offset:1024
	ds_read_b128 v[178:181], v169 offset:2048
	ds_read_b128 v[182:185], v169 offset:3072
	v_add_u32_e32 v169, s58, v148
	ds_read_b128 v[186:189], v169
	ds_read_b128 v[190:193], v169 offset:1024
	ds_read_b128 v[196:199], v169 offset:2048
	ds_read_b128 v[202:205], v169 offset:3072
	s_add_u32 s40, s52, 0x2b0000
	s_addc_u32 s41, s53, 0
	s_mov_b32 m0, s25
	v_lshl_add_u64 v[242:243], s[40:41], 0, v[130:131]
	ds_read_b128 v[206:209], v168 offset:32768
	ds_read_b128 v[210:213], v168 offset:33792
	ds_read_b128 v[214:217], v168 offset:34816
	ds_read_b128 v[218:221], v168 offset:35840
	ds_read_b128 v[222:225], v168 offset:36864
	ds_read_b128 v[226:229], v168 offset:37888
	ds_read_b128 v[230:233], v168 offset:38912
	ds_read_b128 v[234:237], v168 offset:39936
	global_load_lds_dwordx4 v[242:243], off
	v_lshl_add_u64 v[242:243], s[40:41], 0, v[134:135]
	s_mov_b32 m0, s26
	s_nop 0
	global_load_lds_dwordx4 v[242:243], off
	s_waitcnt vmcnt(8)
	s_waitcnt lgkmcnt(0)
	s_setprio 1
	s_barrier
	v_mfma_f32_16x16x32_bf16 v[126:129], v[170:173], v[206:209], v[126:129]
	v_mfma_f32_16x16x32_bf16 v[122:125], v[178:181], v[206:209], v[122:125]
	v_mfma_f32_16x16x32_bf16 v[106:109], v[178:181], v[214:217], v[106:109]
	v_mfma_f32_16x16x32_bf16 v[110:113], v[170:173], v[214:217], v[110:113]
	v_mfma_f32_16x16x32_bf16 v[94:97], v[170:173], v[222:225], v[94:97]
	v_mfma_f32_16x16x32_bf16 v[90:93], v[178:181], v[222:225], v[90:93]
	v_mfma_f32_16x16x32_bf16 v[74:77], v[178:181], v[230:233], v[74:77]
	v_mfma_f32_16x16x32_bf16 v[78:81], v[170:173], v[230:233], v[78:81]
	v_mfma_f32_16x16x32_bf16 v[126:129], v[174:177], v[210:213], v[126:129]
	v_mfma_f32_16x16x32_bf16 v[122:125], v[182:185], v[210:213], v[122:125]
	v_mfma_f32_16x16x32_bf16 v[106:109], v[182:185], v[218:221], v[106:109]
	v_mfma_f32_16x16x32_bf16 v[110:113], v[174:177], v[218:221], v[110:113]
	v_mfma_f32_16x16x32_bf16 v[94:97], v[174:177], v[226:229], v[94:97]
	v_mfma_f32_16x16x32_bf16 v[90:93], v[182:185], v[226:229], v[90:93]
	v_mfma_f32_16x16x32_bf16 v[74:77], v[182:185], v[234:237], v[74:77]
	v_mfma_f32_16x16x32_bf16 v[78:81], v[174:177], v[234:237], v[78:81]
	s_setprio 0
	s_setprio 1
	v_mfma_f32_16x16x32_bf16 v[118:121], v[186:189], v[206:209], v[118:121]
	v_mfma_f32_16x16x32_bf16 v[114:117], v[196:199], v[206:209], v[114:117]
	v_mfma_f32_16x16x32_bf16 v[98:101], v[196:199], v[214:217], v[98:101]
	v_mfma_f32_16x16x32_bf16 v[102:105], v[186:189], v[214:217], v[102:105]
	v_mfma_f32_16x16x32_bf16 v[86:89], v[186:189], v[222:225], v[86:89]
	v_mfma_f32_16x16x32_bf16 v[82:85], v[196:199], v[222:225], v[82:85]
	v_mfma_f32_16x16x32_bf16 v[66:69], v[196:199], v[230:233], v[66:69]
	v_mfma_f32_16x16x32_bf16 v[70:73], v[186:189], v[230:233], v[70:73]
	v_mfma_f32_16x16x32_bf16 v[118:121], v[190:193], v[210:213], v[118:121]
	v_mfma_f32_16x16x32_bf16 v[114:117], v[202:205], v[210:213], v[114:117]
	v_mfma_f32_16x16x32_bf16 v[98:101], v[202:205], v[218:221], v[98:101]
	v_mfma_f32_16x16x32_bf16 v[102:105], v[190:193], v[218:221], v[102:105]
	v_mfma_f32_16x16x32_bf16 v[86:89], v[190:193], v[226:229], v[86:89]
	v_mfma_f32_16x16x32_bf16 v[82:85], v[202:205], v[226:229], v[82:85]
	v_mfma_f32_16x16x32_bf16 v[66:69], v[202:205], v[234:237], v[66:69]
	v_mfma_f32_16x16x32_bf16 v[70:73], v[190:193], v[234:237], v[70:73]
	s_barrier
; #define PG8_STAGE(bufoff, gbase, voff) do { _Pragma("unroll") for (int _i = 0; _i < 2; ++_i) \
;         __builtin_amdgcn_global_load_lds((const unsigned*)((const char*)(gbase) + (voff)[_i]), (PG8_LAS unsigned*)(lds + (bufoff) + ldsw + _i * 8192), 16, 0, 0); } while (0)
; #define PG8_LDA(dst, b, h) do { _Pragma("unroll") for (int m = 0; m < 4; ++m) _Pragma("unroll") for (int k = 0; k < 2; ++k) dst[m][k] = *(const PG8_LAS bf16x8*)(lds + PG8_SA(b, h) + aoff + m * 2048 + k * 1024); } while (0)
; #define PG8_MMA(ai, bj, At, Bt) do { __builtin_amdgcn_s_setprio(1); _Pragma("unroll") for (int m = 0; m < 4; ++m) _Pragma("unroll") for (int n = 0; n < 2; ++n) _Pragma("unroll") for (int k = 0; k < 2; ++k) \
;         acc[ai][bj][m][n] = __builtin_amdgcn_mfma_f32_16x16x32_bf16(Bt[n][k], At[m][k], acc[ai][bj][m][n], 0, 0, 0); __builtin_amdgcn_s_setprio(0); } while (0)
; #define PG8_WAIT_V(n) asm volatile("s_waitcnt vmcnt(" #n ")" ::: "memory")
; #define PG8_WAIT_L(n) asm volatile("s_waitcnt lgkmcnt(" #n ")" ::: "memory")
; #define PG8_BAR __builtin_amdgcn_s_barrier()
; #define PG8_SCHED __builtin_amdgcn_sched_barrier(0)
; template <class Epi, class Sched, bool ALIGN_EPI = false, bool SP2 = false>
; __device__ __forceinline__ void gemm_phase(PG8_LAS unsigned char* lds, const Gemm g, const Sched& S, const Epi& E) {
;     ...
;         for (int t = 0; t < nt; t += 2) {
;             const bool last = (t == nt - 2);
;             const char* a1 = cA + (size_t)(t + 1) * kstep;
;             const char* a2 = last ? nA : cA + (size_t)(t + 2) * kstep; const char* b2 = last ? nB : cB + (size_t)(t + 2) * kstep;
;     ...
;             PG8_LDA(At, 1, 1); PG8_STAGE(PG8_SB(1, 0), b3, voffB); PG8_STAGE(PG8_SB(1, 1), b3 + hstep, voffB); PG8_STAGE(PG8_SA(1, 0), a3, voffA);
;             PG8_WAIT_V(8); PG8_WAIT_L(0); PG8_BAR; PG8_MMA(1, 0, At, B0); PG8_MMA(1, 1, At, B1); PG8_BAR; PG8_SCHED;
	s_setprio 0
	s_add_i32 s40, s57, s3
	v_lshl_add_u64 v[146:147], v[146:147], 0, s[10:11]
	s_mov_b32 m0, s40
	ds_read_b128 v[206:209], v168 offset:49152
	ds_read_b128 v[210:213], v168 offset:50176
	ds_read_b128 v[214:217], v168 offset:51200
	ds_read_b128 v[218:221], v168 offset:52224
	ds_read_b128 v[222:225], v168 offset:53248
	ds_read_b128 v[226:229], v168 offset:54272
	ds_read_b128 v[230:233], v168 offset:55296
	ds_read_b128 v[234:237], v168 offset:56320
	global_load_lds_dwordx4 v[146:147], off
	s_add_i32 m0, s40, 0x2000
	s_add_u32 s40, s50, 0x2b0080
	v_lshl_add_u64 v[146:147], v[194:195], 0, s[10:11]
	s_addc_u32 s41, s51, 0
	s_add_i32 s50, s58, s3
	global_load_lds_dwordx4 v[146:147], off
	v_lshl_add_u64 v[146:147], s[40:41], 0, v[132:133]
	s_mov_b32 m0, s50
	s_nop 0
	global_load_lds_dwordx4 v[146:147], off
	v_lshl_add_u64 v[146:147], s[40:41], 0, v[136:137]
	s_add_i32 m0, s50, 0x2000
	s_nop 0
	global_load_lds_dwordx4 v[146:147], off
	v_lshl_add_u64 v[146:147], v[238:239], 0, s[10:11]
	s_mov_b32 m0, s28
	s_nop 0
	global_load_lds_dwordx4 v[146:147], off
	v_lshl_add_u64 v[146:147], v[240:241], 0, s[10:11]
	s_mov_b32 m0, s29
	s_nop 0
	global_load_lds_dwordx4 v[146:147], off
	s_waitcnt vmcnt(8)
	s_waitcnt lgkmcnt(0)
	s_setprio 1
	s_barrier
	v_mfma_f32_16x16x32_bf16 v[62:65], v[170:173], v[206:209], v[62:65]
	v_mfma_f32_16x16x32_bf16 v[58:61], v[178:181], v[206:209], v[58:61]
	v_mfma_f32_16x16x32_bf16 v[42:45], v[178:181], v[214:217], v[42:45]
	v_mfma_f32_16x16x32_bf16 v[46:49], v[170:173], v[214:217], v[46:49]
	v_mfma_f32_16x16x32_bf16 v[30:33], v[170:173], v[222:225], v[30:33]
	v_mfma_f32_16x16x32_bf16 v[26:29], v[178:181], v[222:225], v[26:29]
	v_mfma_f32_16x16x32_bf16 v[10:13], v[178:181], v[230:233], v[10:13]
	v_mfma_f32_16x16x32_bf16 v[14:17], v[170:173], v[230:233], v[14:17]
	v_mfma_f32_16x16x32_bf16 v[62:65], v[174:177], v[210:213], v[62:65]
	v_mfma_f32_16x16x32_bf16 v[58:61], v[182:185], v[210:213], v[58:61]
	v_mfma_f32_16x16x32_bf16 v[42:45], v[182:185], v[218:221], v[42:45]
	v_mfma_f32_16x16x32_bf16 v[46:49], v[174:177], v[218:221], v[46:49]
	v_mfma_f32_16x16x32_bf16 v[30:33], v[174:177], v[226:229], v[30:33]
	v_mfma_f32_16x16x32_bf16 v[26:29], v[182:185], v[226:229], v[26:29]
	v_mfma_f32_16x16x32_bf16 v[10:13], v[182:185], v[234:237], v[10:13]
	v_mfma_f32_16x16x32_bf16 v[14:17], v[174:177], v[234:237], v[14:17]
	s_setprio 0
	s_setprio 1
	v_mfma_f32_16x16x32_bf16 v[54:57], v[186:189], v[206:209], v[54:57]
	v_mfma_f32_16x16x32_bf16 v[50:53], v[196:199], v[206:209], v[50:53]
	v_mfma_f32_16x16x32_bf16 v[34:37], v[196:199], v[214:217], v[34:37]
	v_mfma_f32_16x16x32_bf16 v[38:41], v[186:189], v[214:217], v[38:41]
	v_mfma_f32_16x16x32_bf16 v[22:25], v[186:189], v[222:225], v[22:25]
	v_mfma_f32_16x16x32_bf16 v[18:21], v[196:199], v[222:225], v[18:21]
	v_mfma_f32_16x16x32_bf16 v[2:5], v[196:199], v[230:233], v[2:5]
	v_mfma_f32_16x16x32_bf16 v[6:9], v[186:189], v[230:233], v[6:9]
	v_mfma_f32_16x16x32_bf16 v[54:57], v[190:193], v[210:213], v[54:57]
	v_mfma_f32_16x16x32_bf16 v[50:53], v[202:205], v[210:213], v[50:53]
	v_mfma_f32_16x16x32_bf16 v[34:37], v[202:205], v[218:221], v[34:37]
	v_mfma_f32_16x16x32_bf16 v[38:41], v[190:193], v[218:221], v[38:41]
	v_mfma_f32_16x16x32_bf16 v[22:25], v[190:193], v[226:229], v[22:25]
	v_mfma_f32_16x16x32_bf16 v[18:21], v[202:205], v[226:229], v[18:21]
	v_mfma_f32_16x16x32_bf16 v[2:5], v[202:205], v[234:237], v[2:5]
	v_mfma_f32_16x16x32_bf16 v[6:9], v[190:193], v[234:237], v[6:9]
	s_barrier
	s_setprio 0
	s_add_i32 s56, s56, 2
	s_add_u32 s54, s54, 0x100
	s_addc_u32 s55, s55, 0
	s_cmpk_gt_u32 s56, 0xa9
	s_mov_b64 s[40:41], s[48:49]
	s_cbranch_scc0 .LBB0_1731
	s_and_b64 vcc, exec, s[12:13]
	s_cbranch_vccz .LBB0_1734
	s_barrier
